# all per-block s_setprio removed, on top of chained MFMA order + 64-bit clears + p-loop pipeline + DPP row sums
# baseline (speedup 1.0000x reference)
.LBB0_60:
	s_add_u32 s42, s6, 0xfff80080
	s_addc_u32 s43, s7, -1
	s_add_i32 s49, 0, 0x10000
	s_cmp_eq_u32 s48, 28
	s_cselect_b32 s45, s13, s43
	s_cselect_b32 s44, s19, s42
	s_cselect_b32 s43, s11, s47
	s_cselect_b32 s42, s41, s46
	s_add_i32 s69, 0, 0x14000
	v_add_u32_e32 v172, s49, v228
	v_add_u32_e32 v184, s69, v228
	ds_read_b128 v[160:163], v172
	ds_read_b128 v[164:167], v172 offset:1024
	ds_read_b128 v[168:171], v172 offset:2048
	ds_read_b128 v[172:175], v172 offset:3072
	ds_read_b128 v[176:179], v184
	ds_read_b128 v[180:183], v184 offset:1024
	ds_read_b128 v[202:205], v184 offset:2048
	ds_read_b128 v[206:209], v184 offset:3072
	v_lshl_add_u64 v[186:187], s[6:7], 0, v[198:199]
	s_add_i32 m0, s56, 0xc000
	ds_read_b128 v[210:213], v229
	ds_read_b128 v[214:217], v229 offset:1024
	ds_read_b128 v[218:221], v229 offset:2048
	ds_read_b128 v[222:225], v229 offset:3072
	ds_read_b128 v[230:233], v229 offset:4096
	ds_read_b128 v[234:237], v229 offset:5120
	ds_read_b128 v[244:247], v229 offset:6144
	ds_read_b128 v[248:251], v229 offset:7168
	global_load_lds_dwordx4 v[186:187], off
	v_lshl_add_u64 v[186:187], s[6:7], 0, v[200:201]
	s_add_i32 m0, s56, 0xe000
	s_nop 0
	global_load_lds_dwordx4 v[186:187], off
	s_waitcnt vmcnt(8)
	s_waitcnt lgkmcnt(0)
	s_barrier
	s_waitcnt lgkmcnt(0)
	v_mfma_f32_16x16x32_bf16 v[156:159], v[160:163], v[210:213], v[156:159]
	v_mfma_f32_16x16x32_bf16 v[156:159], v[164:167], v[214:217], v[156:159]
	v_mfma_f32_16x16x32_bf16 v[140:143], v[160:163], v[218:221], v[140:143]
	v_mfma_f32_16x16x32_bf16 v[140:143], v[164:167], v[222:225], v[140:143]
	v_mfma_f32_16x16x32_bf16 v[124:127], v[160:163], v[230:233], v[124:127]
	v_mfma_f32_16x16x32_bf16 v[124:127], v[164:167], v[234:237], v[124:127]
	v_mfma_f32_16x16x32_bf16 v[108:111], v[160:163], v[244:247], v[108:111]
	v_mfma_f32_16x16x32_bf16 v[108:111], v[164:167], v[248:251], v[108:111]
	v_mfma_f32_16x16x32_bf16 v[152:155], v[168:171], v[210:213], v[152:155]
	v_mfma_f32_16x16x32_bf16 v[152:155], v[172:175], v[214:217], v[152:155]
	v_mfma_f32_16x16x32_bf16 v[136:139], v[168:171], v[218:221], v[136:139]
	v_mfma_f32_16x16x32_bf16 v[136:139], v[172:175], v[222:225], v[136:139]
	v_mfma_f32_16x16x32_bf16 v[120:123], v[168:171], v[230:233], v[120:123]
	v_mfma_f32_16x16x32_bf16 v[120:123], v[172:175], v[234:237], v[120:123]
	v_mfma_f32_16x16x32_bf16 v[104:107], v[168:171], v[244:247], v[104:107]
	v_mfma_f32_16x16x32_bf16 v[104:107], v[172:175], v[248:251], v[104:107]
	v_mfma_f32_16x16x32_bf16 v[148:151], v[176:179], v[210:213], v[148:151]
	v_mfma_f32_16x16x32_bf16 v[148:151], v[180:183], v[214:217], v[148:151]
	v_mfma_f32_16x16x32_bf16 v[132:135], v[176:179], v[218:221], v[132:135]
	v_mfma_f32_16x16x32_bf16 v[132:135], v[180:183], v[222:225], v[132:135]
	v_mfma_f32_16x16x32_bf16 v[116:119], v[176:179], v[230:233], v[116:119]
	v_mfma_f32_16x16x32_bf16 v[116:119], v[180:183], v[234:237], v[116:119]
	v_mfma_f32_16x16x32_bf16 v[100:103], v[176:179], v[244:247], v[100:103]
	v_mfma_f32_16x16x32_bf16 v[100:103], v[180:183], v[248:251], v[100:103]
	v_mfma_f32_16x16x32_bf16 v[144:147], v[202:205], v[210:213], v[144:147]
	v_mfma_f32_16x16x32_bf16 v[144:147], v[206:209], v[214:217], v[144:147]
	v_mfma_f32_16x16x32_bf16 v[128:131], v[202:205], v[218:221], v[128:131]
	v_mfma_f32_16x16x32_bf16 v[128:131], v[206:209], v[222:225], v[128:131]
	v_mfma_f32_16x16x32_bf16 v[112:115], v[202:205], v[230:233], v[112:115]
	v_mfma_f32_16x16x32_bf16 v[112:115], v[206:209], v[234:237], v[112:115]
	v_mfma_f32_16x16x32_bf16 v[96:99], v[202:205], v[244:247], v[96:99]
	v_mfma_f32_16x16x32_bf16 v[96:99], v[206:209], v[248:251], v[96:99]
	s_barrier
	s_add_i32 s49, s49, s89
	v_lshl_add_u64 v[186:187], s[42:43], 0, v[192:193]
	s_mov_b32 m0, s49
	ds_read_b128 v[210:213], v229 offset:16384
	ds_read_b128 v[214:217], v229 offset:17408
	ds_read_b128 v[218:221], v229 offset:18432
	ds_read_b128 v[222:225], v229 offset:19456
	ds_read_b128 v[230:233], v229 offset:20480
	ds_read_b128 v[234:237], v229 offset:21504
	ds_read_b128 v[244:247], v229 offset:22528
	ds_read_b128 v[248:251], v229 offset:23552
	global_load_lds_dwordx4 v[186:187], off
	s_add_i32 m0, s49, 0x2000
	s_add_u32 s50, s42, 0x80000
	v_lshl_add_u64 v[188:189], s[42:43], 0, v[196:197]
	s_addc_u32 s51, s43, 0
	s_add_i32 s49, s69, s89
	global_load_lds_dwordx4 v[188:189], off
	v_lshl_add_u64 v[226:227], s[50:51], 0, v[192:193]
	s_mov_b32 m0, s49
	v_lshl_add_u64 v[238:239], s[44:45], 0, v[194:195]
	global_load_lds_dwordx4 v[226:227], off
	v_lshl_add_u64 v[226:227], s[50:51], 0, v[196:197]
	s_add_i32 m0, s49, 0x2000
	s_nop 0
	global_load_lds_dwordx4 v[226:227], off
	v_lshl_add_u64 v[226:227], s[44:45], 0, v[190:191]
	s_mov_b32 m0, s56
	s_nop 0
	global_load_lds_dwordx4 v[226:227], off
	s_mov_b32 m0, s57
	s_nop 0
	global_load_lds_dwordx4 v[238:239], off
	s_waitcnt vmcnt(8)
	s_waitcnt lgkmcnt(0)
	s_barrier
	s_waitcnt lgkmcnt(0)
	v_mfma_f32_16x16x32_bf16 v[92:95], v[160:163], v[210:213], v[92:95]
	v_mfma_f32_16x16x32_bf16 v[92:95], v[164:167], v[214:217], v[92:95]
	v_mfma_f32_16x16x32_bf16 v[76:79], v[160:163], v[218:221], v[76:79]
	v_mfma_f32_16x16x32_bf16 v[76:79], v[164:167], v[222:225], v[76:79]
	v_mfma_f32_16x16x32_bf16 v[60:63], v[160:163], v[230:233], v[60:63]
	v_mfma_f32_16x16x32_bf16 v[60:63], v[164:167], v[234:237], v[60:63]
	v_mfma_f32_16x16x32_bf16 v[44:47], v[160:163], v[244:247], v[44:47]
	v_mfma_f32_16x16x32_bf16 v[44:47], v[164:167], v[248:251], v[44:47]
	v_mfma_f32_16x16x32_bf16 v[88:91], v[168:171], v[210:213], v[88:91]
	v_mfma_f32_16x16x32_bf16 v[88:91], v[172:175], v[214:217], v[88:91]
	v_mfma_f32_16x16x32_bf16 v[72:75], v[168:171], v[218:221], v[72:75]
	v_mfma_f32_16x16x32_bf16 v[72:75], v[172:175], v[222:225], v[72:75]
	v_mfma_f32_16x16x32_bf16 v[56:59], v[168:171], v[230:233], v[56:59]
	v_mfma_f32_16x16x32_bf16 v[56:59], v[172:175], v[234:237], v[56:59]
	v_mfma_f32_16x16x32_bf16 v[40:43], v[168:171], v[244:247], v[40:43]
	v_mfma_f32_16x16x32_bf16 v[40:43], v[172:175], v[248:251], v[40:43]
	v_mfma_f32_16x16x32_bf16 v[84:87], v[176:179], v[210:213], v[84:87]
	v_mfma_f32_16x16x32_bf16 v[84:87], v[180:183], v[214:217], v[84:87]
	v_mfma_f32_16x16x32_bf16 v[68:71], v[176:179], v[218:221], v[68:71]
	v_mfma_f32_16x16x32_bf16 v[68:71], v[180:183], v[222:225], v[68:71]
	v_mfma_f32_16x16x32_bf16 v[52:55], v[176:179], v[230:233], v[52:55]
	v_mfma_f32_16x16x32_bf16 v[52:55], v[180:183], v[234:237], v[52:55]
	v_mfma_f32_16x16x32_bf16 v[36:39], v[176:179], v[244:247], v[36:39]
	v_mfma_f32_16x16x32_bf16 v[36:39], v[180:183], v[248:251], v[36:39]
	v_mfma_f32_16x16x32_bf16 v[80:83], v[202:205], v[210:213], v[80:83]
	v_mfma_f32_16x16x32_bf16 v[80:83], v[206:209], v[214:217], v[80:83]
	v_mfma_f32_16x16x32_bf16 v[64:67], v[202:205], v[218:221], v[64:67]
	v_mfma_f32_16x16x32_bf16 v[64:67], v[206:209], v[222:225], v[64:67]
	v_mfma_f32_16x16x32_bf16 v[48:51], v[202:205], v[230:233], v[48:51]
	v_mfma_f32_16x16x32_bf16 v[48:51], v[206:209], v[234:237], v[48:51]
	v_mfma_f32_16x16x32_bf16 v[32:35], v[202:205], v[244:247], v[32:35]
	v_mfma_f32_16x16x32_bf16 v[32:35], v[206:209], v[248:251], v[32:35]
	s_barrier
	s_add_i32 s49, 0, 0x18000
	s_add_i32 s50, 0, 0x1c000
	v_add_u32_e32 v172, s49, v228
	v_add_u32_e32 v184, s50, v228
	ds_read_b128 v[160:163], v172
	ds_read_b128 v[164:167], v172 offset:1024
	ds_read_b128 v[168:171], v172 offset:2048
	ds_read_b128 v[172:175], v172 offset:3072
	ds_read_b128 v[176:179], v184
	ds_read_b128 v[180:183], v184 offset:1024
	ds_read_b128 v[202:205], v184 offset:2048
	ds_read_b128 v[206:209], v184 offset:3072
	s_add_u32 s44, s44, 0x80000
	s_addc_u32 s45, s45, 0
	s_mov_b32 m0, s63
	v_lshl_add_u64 v[252:253], s[44:45], 0, v[190:191]
	ds_read_b128 v[210:213], v229 offset:32768
	ds_read_b128 v[214:217], v229 offset:33792
	ds_read_b128 v[218:221], v229 offset:34816
	ds_read_b128 v[222:225], v229 offset:35840
	ds_read_b128 v[230:233], v229 offset:36864
	ds_read_b128 v[234:237], v229 offset:37888
	ds_read_b128 v[244:247], v229 offset:38912
	ds_read_b128 v[248:251], v229 offset:39936
	global_load_lds_dwordx4 v[252:253], off
	v_lshl_add_u64 v[252:253], s[44:45], 0, v[194:195]
	s_mov_b32 m0, s64
	s_nop 0
	global_load_lds_dwordx4 v[252:253], off
	s_waitcnt vmcnt(8)
	s_waitcnt lgkmcnt(0)
	s_barrier
	s_waitcnt lgkmcnt(0)
	v_mfma_f32_16x16x32_bf16 v[156:159], v[160:163], v[210:213], v[156:159]
	v_mfma_f32_16x16x32_bf16 v[156:159], v[164:167], v[214:217], v[156:159]
	v_mfma_f32_16x16x32_bf16 v[140:143], v[160:163], v[218:221], v[140:143]
	v_mfma_f32_16x16x32_bf16 v[140:143], v[164:167], v[222:225], v[140:143]
	v_mfma_f32_16x16x32_bf16 v[124:127], v[160:163], v[230:233], v[124:127]
	v_mfma_f32_16x16x32_bf16 v[124:127], v[164:167], v[234:237], v[124:127]
	v_mfma_f32_16x16x32_bf16 v[108:111], v[160:163], v[244:247], v[108:111]
	v_mfma_f32_16x16x32_bf16 v[108:111], v[164:167], v[248:251], v[108:111]
	v_mfma_f32_16x16x32_bf16 v[152:155], v[168:171], v[210:213], v[152:155]
	v_mfma_f32_16x16x32_bf16 v[152:155], v[172:175], v[214:217], v[152:155]
	v_mfma_f32_16x16x32_bf16 v[136:139], v[168:171], v[218:221], v[136:139]
	v_mfma_f32_16x16x32_bf16 v[136:139], v[172:175], v[222:225], v[136:139]
	v_mfma_f32_16x16x32_bf16 v[120:123], v[168:171], v[230:233], v[120:123]
	v_mfma_f32_16x16x32_bf16 v[120:123], v[172:175], v[234:237], v[120:123]
	v_mfma_f32_16x16x32_bf16 v[104:107], v[168:171], v[244:247], v[104:107]
	v_mfma_f32_16x16x32_bf16 v[104:107], v[172:175], v[248:251], v[104:107]
	v_mfma_f32_16x16x32_bf16 v[148:151], v[176:179], v[210:213], v[148:151]
	v_mfma_f32_16x16x32_bf16 v[148:151], v[180:183], v[214:217], v[148:151]
	v_mfma_f32_16x16x32_bf16 v[132:135], v[176:179], v[218:221], v[132:135]
	v_mfma_f32_16x16x32_bf16 v[132:135], v[180:183], v[222:225], v[132:135]
	v_mfma_f32_16x16x32_bf16 v[116:119], v[176:179], v[230:233], v[116:119]
	v_mfma_f32_16x16x32_bf16 v[116:119], v[180:183], v[234:237], v[116:119]
	v_mfma_f32_16x16x32_bf16 v[100:103], v[176:179], v[244:247], v[100:103]
	v_mfma_f32_16x16x32_bf16 v[100:103], v[180:183], v[248:251], v[100:103]
	v_mfma_f32_16x16x32_bf16 v[144:147], v[202:205], v[210:213], v[144:147]
	v_mfma_f32_16x16x32_bf16 v[144:147], v[206:209], v[214:217], v[144:147]
	v_mfma_f32_16x16x32_bf16 v[128:131], v[202:205], v[218:221], v[128:131]
	v_mfma_f32_16x16x32_bf16 v[128:131], v[206:209], v[222:225], v[128:131]
	v_mfma_f32_16x16x32_bf16 v[112:115], v[202:205], v[230:233], v[112:115]
	v_mfma_f32_16x16x32_bf16 v[112:115], v[206:209], v[234:237], v[112:115]
	v_mfma_f32_16x16x32_bf16 v[96:99], v[202:205], v[244:247], v[96:99]
	v_mfma_f32_16x16x32_bf16 v[96:99], v[206:209], v[248:251], v[96:99]
	s_barrier
	s_add_i32 s44, s49, s89
	v_lshl_add_u64 v[186:187], v[186:187], 0, s[96:97]
	s_mov_b32 m0, s44
	ds_read_b128 v[210:213], v229 offset:49152
	ds_read_b128 v[214:217], v229 offset:50176
	ds_read_b128 v[218:221], v229 offset:51200
	ds_read_b128 v[222:225], v229 offset:52224
	ds_read_b128 v[230:233], v229 offset:53248
	ds_read_b128 v[234:237], v229 offset:54272
	ds_read_b128 v[244:247], v229 offset:55296
	ds_read_b128 v[248:251], v229 offset:56320
	global_load_lds_dwordx4 v[186:187], off
	s_add_i32 m0, s44, 0x2000
	s_add_u32 s42, s42, 0x80080
	v_lshl_add_u64 v[186:187], v[188:189], 0, s[96:97]
	s_addc_u32 s43, s43, 0
	s_add_i32 s44, s50, s89
	global_load_lds_dwordx4 v[186:187], off
	v_lshl_add_u64 v[186:187], s[42:43], 0, v[192:193]
	s_mov_b32 m0, s44
	s_nop 0
	global_load_lds_dwordx4 v[186:187], off
	v_lshl_add_u64 v[186:187], s[42:43], 0, v[196:197]
	s_add_i32 m0, s44, 0x2000
	s_nop 0
	global_load_lds_dwordx4 v[186:187], off
	v_lshl_add_u64 v[186:187], v[226:227], 0, s[96:97]
	s_mov_b32 m0, s65
	s_nop 0
	global_load_lds_dwordx4 v[186:187], off
	v_lshl_add_u64 v[186:187], v[238:239], 0, s[96:97]
	s_mov_b32 m0, s66
	s_nop 0
	global_load_lds_dwordx4 v[186:187], off
	s_waitcnt vmcnt(8)
	s_waitcnt lgkmcnt(0)
	s_barrier
	s_waitcnt lgkmcnt(0)
	v_mfma_f32_16x16x32_bf16 v[92:95], v[160:163], v[210:213], v[92:95]
	v_mfma_f32_16x16x32_bf16 v[92:95], v[164:167], v[214:217], v[92:95]
	v_mfma_f32_16x16x32_bf16 v[76:79], v[160:163], v[218:221], v[76:79]
	v_mfma_f32_16x16x32_bf16 v[76:79], v[164:167], v[222:225], v[76:79]
	v_mfma_f32_16x16x32_bf16 v[60:63], v[160:163], v[230:233], v[60:63]
	v_mfma_f32_16x16x32_bf16 v[60:63], v[164:167], v[234:237], v[60:63]
	v_mfma_f32_16x16x32_bf16 v[44:47], v[160:163], v[244:247], v[44:47]
	v_mfma_f32_16x16x32_bf16 v[44:47], v[164:167], v[248:251], v[44:47]
	v_mfma_f32_16x16x32_bf16 v[88:91], v[168:171], v[210:213], v[88:91]
	v_mfma_f32_16x16x32_bf16 v[88:91], v[172:175], v[214:217], v[88:91]
	v_mfma_f32_16x16x32_bf16 v[72:75], v[168:171], v[218:221], v[72:75]
	v_mfma_f32_16x16x32_bf16 v[72:75], v[172:175], v[222:225], v[72:75]
	v_mfma_f32_16x16x32_bf16 v[56:59], v[168:171], v[230:233], v[56:59]
	v_mfma_f32_16x16x32_bf16 v[56:59], v[172:175], v[234:237], v[56:59]
	v_mfma_f32_16x16x32_bf16 v[40:43], v[168:171], v[244:247], v[40:43]
	v_mfma_f32_16x16x32_bf16 v[40:43], v[172:175], v[248:251], v[40:43]
	v_mfma_f32_16x16x32_bf16 v[84:87], v[176:179], v[210:213], v[84:87]
	v_mfma_f32_16x16x32_bf16 v[84:87], v[180:183], v[214:217], v[84:87]
	v_mfma_f32_16x16x32_bf16 v[68:71], v[176:179], v[218:221], v[68:71]
	v_mfma_f32_16x16x32_bf16 v[68:71], v[180:183], v[222:225], v[68:71]
	v_mfma_f32_16x16x32_bf16 v[52:55], v[176:179], v[230:233], v[52:55]
	v_mfma_f32_16x16x32_bf16 v[52:55], v[180:183], v[234:237], v[52:55]
	v_mfma_f32_16x16x32_bf16 v[36:39], v[176:179], v[244:247], v[36:39]
	v_mfma_f32_16x16x32_bf16 v[36:39], v[180:183], v[248:251], v[36:39]
	v_mfma_f32_16x16x32_bf16 v[80:83], v[202:205], v[210:213], v[80:83]
	v_mfma_f32_16x16x32_bf16 v[80:83], v[206:209], v[214:217], v[80:83]
	v_mfma_f32_16x16x32_bf16 v[64:67], v[202:205], v[218:221], v[64:67]
	v_mfma_f32_16x16x32_bf16 v[64:67], v[206:209], v[222:225], v[64:67]
	v_mfma_f32_16x16x32_bf16 v[48:51], v[202:205], v[230:233], v[48:51]
	v_mfma_f32_16x16x32_bf16 v[48:51], v[206:209], v[234:237], v[48:51]
	v_mfma_f32_16x16x32_bf16 v[32:35], v[202:205], v[244:247], v[32:35]
	v_mfma_f32_16x16x32_bf16 v[32:35], v[206:209], v[248:251], v[32:35]
	s_barrier
	s_add_i32 s48, s48, 2
	s_add_u32 s6, s6, 0x100
	s_addc_u32 s7, s7, 0
	s_add_u32 s46, s46, 0x100
	s_addc_u32 s47, s47, 0
	s_cmp_gt_u32 s48, 29
	s_cbranch_scc0 .LBB0_60
	s_and_b64 vcc, exec, s[86:87]
	s_cbranch_vccz .LBB0_63
	s_barrier

.LBB0_170:
	s_add_u32 s42, s40, 0xfff80080
	s_addc_u32 s43, s41, -1
	s_add_i32 s65, 0, 0x10000
	s_cmp_eq_u32 s64, 28
	s_cselect_b32 s45, s11, s43
	s_cselect_b32 s44, s17, s42
	v_add_u32_e32 v150, s65, v152
	s_cselect_b32 s43, s7, s63
	s_cselect_b32 s42, s19, s57
	s_add_i32 s68, 0, 0x14000
	ds_read_b128 v[128:131], v150
	ds_read_b128 v[142:145], v150 offset:1024
	ds_read_b128 v[146:149], v150 offset:2048
	ds_read_b128 v[154:157], v150 offset:3072
	v_add_u32_e32 v150, s68, v152
	ds_read_b128 v[158:161], v150
	ds_read_b128 v[162:165], v150 offset:1024
	ds_read_b128 v[166:169], v150 offset:2048
	ds_read_b128 v[170:173], v150 offset:3072
	v_lshl_add_u64 v[150:151], s[40:41], 0, v[138:139]
	s_add_i32 m0, s46, 0xc000
	ds_read_b128 v[174:177], v153
	ds_read_b128 v[178:181], v153 offset:1024
	ds_read_b128 v[190:193], v153 offset:2048
	ds_read_b128 v[194:197], v153 offset:3072
	ds_read_b128 v[198:201], v153 offset:4096
	ds_read_b128 v[202:205], v153 offset:5120
	ds_read_b128 v[206:209], v153 offset:6144
	ds_read_b128 v[210:213], v153 offset:7168
	global_load_lds_dwordx4 v[150:151], off
	v_lshl_add_u64 v[150:151], s[40:41], 0, v[140:141]
	s_add_i32 m0, s46, 0xe000
	s_nop 0
	global_load_lds_dwordx4 v[150:151], off
	s_waitcnt vmcnt(8)
	s_waitcnt lgkmcnt(0)
	s_barrier
	s_waitcnt lgkmcnt(0)
	v_mfma_f32_16x16x32_bf16 v[116:119], v[128:131], v[174:177], v[116:119]
	v_mfma_f32_16x16x32_bf16 v[116:119], v[142:145], v[178:181], v[116:119]
	v_mfma_f32_16x16x32_bf16 v[108:111], v[128:131], v[190:193], v[108:111]
	v_mfma_f32_16x16x32_bf16 v[108:111], v[142:145], v[194:197], v[108:111]
	v_mfma_f32_16x16x32_bf16 v[92:95], v[128:131], v[198:201], v[92:95]
	v_mfma_f32_16x16x32_bf16 v[92:95], v[142:145], v[202:205], v[92:95]
	v_mfma_f32_16x16x32_bf16 v[76:79], v[128:131], v[206:209], v[76:79]
	v_mfma_f32_16x16x32_bf16 v[76:79], v[142:145], v[210:213], v[76:79]
	v_mfma_f32_16x16x32_bf16 v[112:115], v[146:149], v[174:177], v[112:115]
	v_mfma_f32_16x16x32_bf16 v[112:115], v[154:157], v[178:181], v[112:115]
	v_mfma_f32_16x16x32_bf16 v[96:99], v[146:149], v[190:193], v[96:99]
	v_mfma_f32_16x16x32_bf16 v[96:99], v[154:157], v[194:197], v[96:99]
	v_mfma_f32_16x16x32_bf16 v[80:83], v[146:149], v[198:201], v[80:83]
	v_mfma_f32_16x16x32_bf16 v[80:83], v[154:157], v[202:205], v[80:83]
	v_mfma_f32_16x16x32_bf16 v[64:67], v[146:149], v[206:209], v[64:67]
	v_mfma_f32_16x16x32_bf16 v[64:67], v[154:157], v[210:213], v[64:67]
	v_mfma_f32_16x16x32_bf16 v[124:127], v[158:161], v[174:177], v[124:127]
	v_mfma_f32_16x16x32_bf16 v[124:127], v[162:165], v[178:181], v[124:127]
	v_mfma_f32_16x16x32_bf16 v[104:107], v[158:161], v[190:193], v[104:107]
	v_mfma_f32_16x16x32_bf16 v[104:107], v[162:165], v[194:197], v[104:107]
	v_mfma_f32_16x16x32_bf16 v[88:91], v[158:161], v[198:201], v[88:91]
	v_mfma_f32_16x16x32_bf16 v[88:91], v[162:165], v[202:205], v[88:91]
	v_mfma_f32_16x16x32_bf16 v[72:75], v[158:161], v[206:209], v[72:75]
	v_mfma_f32_16x16x32_bf16 v[72:75], v[162:165], v[210:213], v[72:75]
	v_mfma_f32_16x16x32_bf16 v[120:123], v[166:169], v[174:177], v[120:123]
	v_mfma_f32_16x16x32_bf16 v[120:123], v[170:173], v[178:181], v[120:123]
	v_mfma_f32_16x16x32_bf16 v[100:103], v[166:169], v[190:193], v[100:103]
	v_mfma_f32_16x16x32_bf16 v[100:103], v[170:173], v[194:197], v[100:103]
	v_mfma_f32_16x16x32_bf16 v[84:87], v[166:169], v[198:201], v[84:87]
	v_mfma_f32_16x16x32_bf16 v[84:87], v[170:173], v[202:205], v[84:87]
	v_mfma_f32_16x16x32_bf16 v[68:71], v[166:169], v[206:209], v[68:71]
	v_mfma_f32_16x16x32_bf16 v[68:71], v[170:173], v[210:213], v[68:71]
	s_barrier
	s_add_i32 s65, s65, s89
	v_lshl_add_u64 v[150:151], s[42:43], 0, v[184:185]
	s_mov_b32 m0, s65
	ds_read_b128 v[174:177], v153 offset:16384
	ds_read_b128 v[178:181], v153 offset:17408
	ds_read_b128 v[190:193], v153 offset:18432
	ds_read_b128 v[194:197], v153 offset:19456
	ds_read_b128 v[198:201], v153 offset:20480
	ds_read_b128 v[202:205], v153 offset:21504
	ds_read_b128 v[206:209], v153 offset:22528
	ds_read_b128 v[210:213], v153 offset:23552
	global_load_lds_dwordx4 v[150:151], off
	s_add_i32 m0, s65, 0x2000
	s_add_u32 s66, s42, 0x80000
	v_lshl_add_u64 v[182:183], s[42:43], 0, v[136:137]
	s_addc_u32 s67, s43, 0
	s_add_i32 s65, s68, s89
	global_load_lds_dwordx4 v[182:183], off
	v_lshl_add_u64 v[186:187], s[66:67], 0, v[184:185]
	s_mov_b32 m0, s65
	v_lshl_add_u64 v[188:189], s[44:45], 0, v[134:135]
	global_load_lds_dwordx4 v[186:187], off
	v_lshl_add_u64 v[186:187], s[66:67], 0, v[136:137]
	s_add_i32 m0, s65, 0x2000
	s_nop 0
	global_load_lds_dwordx4 v[186:187], off
	v_lshl_add_u64 v[186:187], s[44:45], 0, v[132:133]
	s_mov_b32 m0, s46
	s_nop 0
	global_load_lds_dwordx4 v[186:187], off
	s_mov_b32 m0, s47
	s_nop 0
	global_load_lds_dwordx4 v[188:189], off
	s_waitcnt vmcnt(8)
	s_waitcnt lgkmcnt(0)
	s_barrier
	s_waitcnt lgkmcnt(0)
	v_mfma_f32_16x16x32_bf16 v[60:63], v[128:131], v[174:177], v[60:63]
	v_mfma_f32_16x16x32_bf16 v[60:63], v[142:145], v[178:181], v[60:63]
	v_mfma_f32_16x16x32_bf16 v[44:47], v[128:131], v[190:193], v[44:47]
	v_mfma_f32_16x16x32_bf16 v[44:47], v[142:145], v[194:197], v[44:47]
	v_mfma_f32_16x16x32_bf16 v[28:31], v[128:131], v[198:201], v[28:31]
	v_mfma_f32_16x16x32_bf16 v[28:31], v[142:145], v[202:205], v[28:31]
	v_mfma_f32_16x16x32_bf16 v[12:15], v[128:131], v[206:209], v[12:15]
	v_mfma_f32_16x16x32_bf16 v[12:15], v[142:145], v[210:213], v[12:15]
	v_mfma_f32_16x16x32_bf16 v[48:51], v[146:149], v[174:177], v[48:51]
	v_mfma_f32_16x16x32_bf16 v[48:51], v[154:157], v[178:181], v[48:51]
	v_mfma_f32_16x16x32_bf16 v[32:35], v[146:149], v[190:193], v[32:35]
	v_mfma_f32_16x16x32_bf16 v[32:35], v[154:157], v[194:197], v[32:35]
	v_mfma_f32_16x16x32_bf16 v[16:19], v[146:149], v[198:201], v[16:19]
	v_mfma_f32_16x16x32_bf16 v[16:19], v[154:157], v[202:205], v[16:19]
	v_mfma_f32_16x16x32_bf16 v[0:3], v[146:149], v[206:209], v[0:3]
	v_mfma_f32_16x16x32_bf16 v[0:3], v[154:157], v[210:213], v[0:3]
	v_mfma_f32_16x16x32_bf16 v[56:59], v[158:161], v[174:177], v[56:59]
	v_mfma_f32_16x16x32_bf16 v[56:59], v[162:165], v[178:181], v[56:59]
	v_mfma_f32_16x16x32_bf16 v[40:43], v[158:161], v[190:193], v[40:43]
	v_mfma_f32_16x16x32_bf16 v[40:43], v[162:165], v[194:197], v[40:43]
	v_mfma_f32_16x16x32_bf16 v[24:27], v[158:161], v[198:201], v[24:27]
	v_mfma_f32_16x16x32_bf16 v[24:27], v[162:165], v[202:205], v[24:27]
	v_mfma_f32_16x16x32_bf16 v[8:11], v[158:161], v[206:209], v[8:11]
	v_mfma_f32_16x16x32_bf16 v[8:11], v[162:165], v[210:213], v[8:11]
	v_mfma_f32_16x16x32_bf16 v[52:55], v[166:169], v[174:177], v[52:55]
	v_mfma_f32_16x16x32_bf16 v[52:55], v[170:173], v[178:181], v[52:55]
	v_mfma_f32_16x16x32_bf16 v[36:39], v[166:169], v[190:193], v[36:39]
	v_mfma_f32_16x16x32_bf16 v[36:39], v[170:173], v[194:197], v[36:39]
	v_mfma_f32_16x16x32_bf16 v[20:23], v[166:169], v[198:201], v[20:23]
	v_mfma_f32_16x16x32_bf16 v[20:23], v[170:173], v[202:205], v[20:23]
	v_mfma_f32_16x16x32_bf16 v[4:7], v[166:169], v[206:209], v[4:7]
	v_mfma_f32_16x16x32_bf16 v[4:7], v[170:173], v[210:213], v[4:7]
	s_barrier
	s_add_i32 s65, 0, 0x18000
	s_add_i32 s66, 0, 0x1c000
	v_add_u32_e32 v154, s65, v152
	v_add_u32_e32 v170, s66, v152
	ds_read_b128 v[128:131], v154
	ds_read_b128 v[142:145], v154 offset:1024
	ds_read_b128 v[146:149], v154 offset:2048
	ds_read_b128 v[154:157], v154 offset:3072
	ds_read_b128 v[158:161], v170
	ds_read_b128 v[162:165], v170 offset:1024
	ds_read_b128 v[166:169], v170 offset:2048
	ds_read_b128 v[170:173], v170 offset:3072
	s_add_u32 s44, s44, 0x80000
	s_addc_u32 s45, s45, 0
	s_mov_b32 m0, s48
	v_lshl_add_u64 v[214:215], s[44:45], 0, v[132:133]
	ds_read_b128 v[174:177], v153 offset:32768
	ds_read_b128 v[178:181], v153 offset:33792
	ds_read_b128 v[190:193], v153 offset:34816
	ds_read_b128 v[194:197], v153 offset:35840
	ds_read_b128 v[198:201], v153 offset:36864
	ds_read_b128 v[202:205], v153 offset:37888
	ds_read_b128 v[206:209], v153 offset:38912
	ds_read_b128 v[210:213], v153 offset:39936
	global_load_lds_dwordx4 v[214:215], off
	v_lshl_add_u64 v[214:215], s[44:45], 0, v[134:135]
	s_mov_b32 m0, s49
	s_nop 0
	global_load_lds_dwordx4 v[214:215], off
	s_waitcnt vmcnt(8)
	s_waitcnt lgkmcnt(0)
	s_barrier
	s_waitcnt lgkmcnt(0)
	v_mfma_f32_16x16x32_bf16 v[116:119], v[128:131], v[174:177], v[116:119]
	v_mfma_f32_16x16x32_bf16 v[116:119], v[142:145], v[178:181], v[116:119]
	v_mfma_f32_16x16x32_bf16 v[108:111], v[128:131], v[190:193], v[108:111]
	v_mfma_f32_16x16x32_bf16 v[108:111], v[142:145], v[194:197], v[108:111]
	v_mfma_f32_16x16x32_bf16 v[92:95], v[128:131], v[198:201], v[92:95]
	v_mfma_f32_16x16x32_bf16 v[92:95], v[142:145], v[202:205], v[92:95]
	v_mfma_f32_16x16x32_bf16 v[76:79], v[128:131], v[206:209], v[76:79]
	v_mfma_f32_16x16x32_bf16 v[76:79], v[142:145], v[210:213], v[76:79]
	v_mfma_f32_16x16x32_bf16 v[112:115], v[146:149], v[174:177], v[112:115]
	v_mfma_f32_16x16x32_bf16 v[112:115], v[154:157], v[178:181], v[112:115]
	v_mfma_f32_16x16x32_bf16 v[96:99], v[146:149], v[190:193], v[96:99]
	v_mfma_f32_16x16x32_bf16 v[96:99], v[154:157], v[194:197], v[96:99]
	v_mfma_f32_16x16x32_bf16 v[80:83], v[146:149], v[198:201], v[80:83]
	v_mfma_f32_16x16x32_bf16 v[80:83], v[154:157], v[202:205], v[80:83]
	v_mfma_f32_16x16x32_bf16 v[64:67], v[146:149], v[206:209], v[64:67]
	v_mfma_f32_16x16x32_bf16 v[64:67], v[154:157], v[210:213], v[64:67]
	v_mfma_f32_16x16x32_bf16 v[124:127], v[158:161], v[174:177], v[124:127]
	v_mfma_f32_16x16x32_bf16 v[124:127], v[162:165], v[178:181], v[124:127]
	v_mfma_f32_16x16x32_bf16 v[104:107], v[158:161], v[190:193], v[104:107]
	v_mfma_f32_16x16x32_bf16 v[104:107], v[162:165], v[194:197], v[104:107]
	v_mfma_f32_16x16x32_bf16 v[88:91], v[158:161], v[198:201], v[88:91]
	v_mfma_f32_16x16x32_bf16 v[88:91], v[162:165], v[202:205], v[88:91]
	v_mfma_f32_16x16x32_bf16 v[72:75], v[158:161], v[206:209], v[72:75]
	v_mfma_f32_16x16x32_bf16 v[72:75], v[162:165], v[210:213], v[72:75]
	v_mfma_f32_16x16x32_bf16 v[120:123], v[166:169], v[174:177], v[120:123]
	v_mfma_f32_16x16x32_bf16 v[120:123], v[170:173], v[178:181], v[120:123]
	v_mfma_f32_16x16x32_bf16 v[100:103], v[166:169], v[190:193], v[100:103]
	v_mfma_f32_16x16x32_bf16 v[100:103], v[170:173], v[194:197], v[100:103]
	v_mfma_f32_16x16x32_bf16 v[84:87], v[166:169], v[198:201], v[84:87]
	v_mfma_f32_16x16x32_bf16 v[84:87], v[170:173], v[202:205], v[84:87]
	v_mfma_f32_16x16x32_bf16 v[68:71], v[166:169], v[206:209], v[68:71]
	v_mfma_f32_16x16x32_bf16 v[68:71], v[170:173], v[210:213], v[68:71]
	s_barrier
	s_add_i32 s44, s65, s89
	v_lshl_add_u64 v[150:151], v[150:151], 0, s[96:97]
	s_mov_b32 m0, s44
	ds_read_b128 v[174:177], v153 offset:49152
	ds_read_b128 v[178:181], v153 offset:50176
	ds_read_b128 v[190:193], v153 offset:51200
	ds_read_b128 v[194:197], v153 offset:52224
	ds_read_b128 v[198:201], v153 offset:53248
	ds_read_b128 v[202:205], v153 offset:54272
	ds_read_b128 v[206:209], v153 offset:55296
	ds_read_b128 v[210:213], v153 offset:56320
	global_load_lds_dwordx4 v[150:151], off
	s_add_i32 m0, s44, 0x2000
	s_add_u32 s42, s42, 0x80080
	v_lshl_add_u64 v[150:151], v[182:183], 0, s[96:97]
	s_addc_u32 s43, s43, 0
	s_add_i32 s44, s66, s89
	global_load_lds_dwordx4 v[150:151], off
	v_lshl_add_u64 v[150:151], s[42:43], 0, v[184:185]
	s_mov_b32 m0, s44
	s_nop 0
	global_load_lds_dwordx4 v[150:151], off
	v_lshl_add_u64 v[150:151], s[42:43], 0, v[136:137]
	s_add_i32 m0, s44, 0x2000
	s_nop 0
	global_load_lds_dwordx4 v[150:151], off
	v_lshl_add_u64 v[150:151], v[186:187], 0, s[96:97]
	s_mov_b32 m0, s50
	s_nop 0
	global_load_lds_dwordx4 v[150:151], off
	v_lshl_add_u64 v[150:151], v[188:189], 0, s[96:97]
	s_mov_b32 m0, s51
	s_nop 0
	global_load_lds_dwordx4 v[150:151], off
	s_waitcnt vmcnt(8)
	s_waitcnt lgkmcnt(0)
	s_barrier
	s_waitcnt lgkmcnt(0)
	v_mfma_f32_16x16x32_bf16 v[60:63], v[128:131], v[174:177], v[60:63]
	v_mfma_f32_16x16x32_bf16 v[60:63], v[142:145], v[178:181], v[60:63]
	v_mfma_f32_16x16x32_bf16 v[44:47], v[128:131], v[190:193], v[44:47]
	v_mfma_f32_16x16x32_bf16 v[44:47], v[142:145], v[194:197], v[44:47]
	v_mfma_f32_16x16x32_bf16 v[28:31], v[128:131], v[198:201], v[28:31]
	v_mfma_f32_16x16x32_bf16 v[28:31], v[142:145], v[202:205], v[28:31]
	v_mfma_f32_16x16x32_bf16 v[12:15], v[128:131], v[206:209], v[12:15]
	v_mfma_f32_16x16x32_bf16 v[12:15], v[142:145], v[210:213], v[12:15]
	v_mfma_f32_16x16x32_bf16 v[48:51], v[146:149], v[174:177], v[48:51]
	v_mfma_f32_16x16x32_bf16 v[48:51], v[154:157], v[178:181], v[48:51]
	v_mfma_f32_16x16x32_bf16 v[32:35], v[146:149], v[190:193], v[32:35]
	v_mfma_f32_16x16x32_bf16 v[32:35], v[154:157], v[194:197], v[32:35]
	v_mfma_f32_16x16x32_bf16 v[16:19], v[146:149], v[198:201], v[16:19]
	v_mfma_f32_16x16x32_bf16 v[16:19], v[154:157], v[202:205], v[16:19]
	v_mfma_f32_16x16x32_bf16 v[0:3], v[146:149], v[206:209], v[0:3]
	v_mfma_f32_16x16x32_bf16 v[0:3], v[154:157], v[210:213], v[0:3]
	v_mfma_f32_16x16x32_bf16 v[56:59], v[158:161], v[174:177], v[56:59]
	v_mfma_f32_16x16x32_bf16 v[56:59], v[162:165], v[178:181], v[56:59]
	v_mfma_f32_16x16x32_bf16 v[40:43], v[158:161], v[190:193], v[40:43]
	v_mfma_f32_16x16x32_bf16 v[40:43], v[162:165], v[194:197], v[40:43]
	v_mfma_f32_16x16x32_bf16 v[24:27], v[158:161], v[198:201], v[24:27]
	v_mfma_f32_16x16x32_bf16 v[24:27], v[162:165], v[202:205], v[24:27]
	v_mfma_f32_16x16x32_bf16 v[8:11], v[158:161], v[206:209], v[8:11]
	v_mfma_f32_16x16x32_bf16 v[8:11], v[162:165], v[210:213], v[8:11]
	v_mfma_f32_16x16x32_bf16 v[52:55], v[166:169], v[174:177], v[52:55]
	v_mfma_f32_16x16x32_bf16 v[52:55], v[170:173], v[178:181], v[52:55]
	v_mfma_f32_16x16x32_bf16 v[36:39], v[166:169], v[190:193], v[36:39]
	v_mfma_f32_16x16x32_bf16 v[36:39], v[170:173], v[194:197], v[36:39]
	v_mfma_f32_16x16x32_bf16 v[20:23], v[166:169], v[198:201], v[20:23]
	v_mfma_f32_16x16x32_bf16 v[20:23], v[170:173], v[202:205], v[20:23]
	v_mfma_f32_16x16x32_bf16 v[4:7], v[166:169], v[206:209], v[4:7]
	v_mfma_f32_16x16x32_bf16 v[4:7], v[170:173], v[210:213], v[4:7]
	s_barrier
	s_add_i32 s64, s64, 2
	s_add_u32 s40, s40, 0x100
	s_addc_u32 s41, s41, 0
	s_add_u32 s57, s57, 0x100
	s_addc_u32 s63, s63, 0
	s_cmp_gt_u32 s64, 29
	s_cbranch_scc0 .LBB0_170
	s_and_b64 vcc, exec, s[86:87]
	s_cbranch_vccz .LBB0_173
	s_barrier

.LBB0_244:
	s_add_u32 s18, s6, 0xfff80080
	s_addc_u32 s19, s7, -1
	s_add_i32 s56, 0, 0x10000
	s_cmp_eq_u32 s51, 28
	s_cselect_b32 s31, s11, s19
	s_cselect_b32 s30, s47, s18
	v_add_u32_e32 v172, s56, v174
	s_cselect_b32 s19, s9, s50
	s_cselect_b32 s18, s48, s49
	s_add_i32 s63, 0, 0x14000
	ds_read_b128 v[176:179], v172
	ds_read_b128 v[180:183], v172 offset:1024
	ds_read_b128 v[190:193], v172 offset:2048
	ds_read_b128 v[194:197], v172 offset:3072
	v_add_u32_e32 v172, s63, v174
	ds_read_b128 v[198:201], v172
	ds_read_b128 v[202:205], v172 offset:1024
	ds_read_b128 v[206:209], v172 offset:2048
	ds_read_b128 v[210:213], v172 offset:3072
	v_lshl_add_u64 v[172:173], s[6:7], 0, v[168:169]
	s_add_i32 m0, s17, 0xc000
	ds_read_b128 v[214:217], v175
	ds_read_b128 v[218:221], v175 offset:1024
	ds_read_b128 v[222:225], v175 offset:2048
	ds_read_b128 v[226:229], v175 offset:3072
	ds_read_b128 v[230:233], v175 offset:4096
	ds_read_b128 v[234:237], v175 offset:5120
	ds_read_b128 v[244:247], v175 offset:6144
	ds_read_b128 v[248:251], v175 offset:7168
	global_load_lds_dwordx4 v[172:173], off
	v_lshl_add_u64 v[172:173], s[6:7], 0, v[170:171]
	s_add_i32 m0, s17, 0xe000
	s_nop 0
	global_load_lds_dwordx4 v[172:173], off
	s_waitcnt vmcnt(8)
	s_waitcnt lgkmcnt(0)
	s_barrier
	s_waitcnt lgkmcnt(0)
	v_mfma_f32_16x16x32_bf16 v[156:159], v[176:179], v[214:217], v[156:159]
	v_mfma_f32_16x16x32_bf16 v[156:159], v[180:183], v[218:221], v[156:159]
	v_mfma_f32_16x16x32_bf16 v[148:151], v[176:179], v[222:225], v[148:151]
	v_mfma_f32_16x16x32_bf16 v[148:151], v[180:183], v[226:229], v[148:151]
	v_mfma_f32_16x16x32_bf16 v[132:135], v[176:179], v[230:233], v[132:135]
	v_mfma_f32_16x16x32_bf16 v[132:135], v[180:183], v[234:237], v[132:135]
	v_mfma_f32_16x16x32_bf16 v[116:119], v[176:179], v[244:247], v[116:119]
	v_mfma_f32_16x16x32_bf16 v[116:119], v[180:183], v[248:251], v[116:119]
	v_mfma_f32_16x16x32_bf16 v[152:155], v[190:193], v[214:217], v[152:155]
	v_mfma_f32_16x16x32_bf16 v[152:155], v[194:197], v[218:221], v[152:155]
	v_mfma_f32_16x16x32_bf16 v[140:143], v[190:193], v[222:225], v[140:143]
	v_mfma_f32_16x16x32_bf16 v[140:143], v[194:197], v[226:229], v[140:143]
	v_mfma_f32_16x16x32_bf16 v[124:127], v[190:193], v[230:233], v[124:127]
	v_mfma_f32_16x16x32_bf16 v[124:127], v[194:197], v[234:237], v[124:127]
	v_mfma_f32_16x16x32_bf16 v[108:111], v[190:193], v[244:247], v[108:111]
	v_mfma_f32_16x16x32_bf16 v[108:111], v[194:197], v[248:251], v[108:111]
	v_mfma_f32_16x16x32_bf16 v[144:147], v[198:201], v[214:217], v[144:147]
	v_mfma_f32_16x16x32_bf16 v[144:147], v[202:205], v[218:221], v[144:147]
	v_mfma_f32_16x16x32_bf16 v[128:131], v[198:201], v[222:225], v[128:131]
	v_mfma_f32_16x16x32_bf16 v[128:131], v[202:205], v[226:229], v[128:131]
	v_mfma_f32_16x16x32_bf16 v[112:115], v[198:201], v[230:233], v[112:115]
	v_mfma_f32_16x16x32_bf16 v[112:115], v[202:205], v[234:237], v[112:115]
	v_mfma_f32_16x16x32_bf16 v[100:103], v[198:201], v[244:247], v[100:103]
	v_mfma_f32_16x16x32_bf16 v[100:103], v[202:205], v[248:251], v[100:103]
	v_mfma_f32_16x16x32_bf16 v[136:139], v[206:209], v[214:217], v[136:139]
	v_mfma_f32_16x16x32_bf16 v[136:139], v[210:213], v[218:221], v[136:139]
	v_mfma_f32_16x16x32_bf16 v[120:123], v[206:209], v[222:225], v[120:123]
	v_mfma_f32_16x16x32_bf16 v[120:123], v[210:213], v[226:229], v[120:123]
	v_mfma_f32_16x16x32_bf16 v[104:107], v[206:209], v[230:233], v[104:107]
	v_mfma_f32_16x16x32_bf16 v[104:107], v[210:213], v[234:237], v[104:107]
	v_mfma_f32_16x16x32_bf16 v[96:99], v[206:209], v[244:247], v[96:99]
	v_mfma_f32_16x16x32_bf16 v[96:99], v[210:213], v[248:251], v[96:99]
	s_barrier
	s_add_i32 s56, s56, s89
	v_lshl_add_u64 v[172:173], s[18:19], 0, v[164:165]
	s_mov_b32 m0, s56
	ds_read_b128 v[214:217], v175 offset:16384
	ds_read_b128 v[218:221], v175 offset:17408
	ds_read_b128 v[222:225], v175 offset:18432
	ds_read_b128 v[226:229], v175 offset:19456
	ds_read_b128 v[230:233], v175 offset:20480
	ds_read_b128 v[234:237], v175 offset:21504
	ds_read_b128 v[244:247], v175 offset:22528
	ds_read_b128 v[248:251], v175 offset:23552
	global_load_lds_dwordx4 v[172:173], off
	s_add_i32 m0, s56, 0x2000
	s_add_u32 s56, s18, 0x80000
	v_lshl_add_u64 v[186:187], s[18:19], 0, v[160:161]
	s_addc_u32 s57, s19, 0
	s_add_i32 s63, s63, s89
	global_load_lds_dwordx4 v[186:187], off
	v_lshl_add_u64 v[188:189], s[56:57], 0, v[164:165]
	s_mov_b32 m0, s63
	v_lshl_add_u64 v[238:239], s[30:31], 0, v[162:163]
	global_load_lds_dwordx4 v[188:189], off
	v_lshl_add_u64 v[188:189], s[56:57], 0, v[160:161]
	s_add_i32 m0, s63, 0x2000
	s_nop 0
	global_load_lds_dwordx4 v[188:189], off
	v_lshl_add_u64 v[188:189], s[30:31], 0, v[166:167]
	s_mov_b32 m0, s17
	s_nop 0
	global_load_lds_dwordx4 v[188:189], off
	s_mov_b32 m0, s39
	s_nop 0
	global_load_lds_dwordx4 v[238:239], off
	s_waitcnt vmcnt(8)
	s_waitcnt lgkmcnt(0)
	s_barrier
	s_waitcnt lgkmcnt(0)
	v_mfma_f32_16x16x32_bf16 v[92:95], v[176:179], v[214:217], v[92:95]
	v_mfma_f32_16x16x32_bf16 v[92:95], v[180:183], v[218:221], v[92:95]
	v_mfma_f32_16x16x32_bf16 v[84:87], v[176:179], v[222:225], v[84:87]
	v_mfma_f32_16x16x32_bf16 v[84:87], v[180:183], v[226:229], v[84:87]
	v_mfma_f32_16x16x32_bf16 v[68:71], v[176:179], v[230:233], v[68:71]
	v_mfma_f32_16x16x32_bf16 v[68:71], v[180:183], v[234:237], v[68:71]
	v_mfma_f32_16x16x32_bf16 v[52:55], v[176:179], v[244:247], v[52:55]
	v_mfma_f32_16x16x32_bf16 v[52:55], v[180:183], v[248:251], v[52:55]
	v_mfma_f32_16x16x32_bf16 v[88:91], v[190:193], v[214:217], v[88:91]
	v_mfma_f32_16x16x32_bf16 v[88:91], v[194:197], v[218:221], v[88:91]
	v_mfma_f32_16x16x32_bf16 v[76:79], v[190:193], v[222:225], v[76:79]
	v_mfma_f32_16x16x32_bf16 v[76:79], v[194:197], v[226:229], v[76:79]
	v_mfma_f32_16x16x32_bf16 v[60:63], v[190:193], v[230:233], v[60:63]
	v_mfma_f32_16x16x32_bf16 v[60:63], v[194:197], v[234:237], v[60:63]
	v_mfma_f32_16x16x32_bf16 v[44:47], v[190:193], v[244:247], v[44:47]
	v_mfma_f32_16x16x32_bf16 v[44:47], v[194:197], v[248:251], v[44:47]
	v_mfma_f32_16x16x32_bf16 v[80:83], v[198:201], v[214:217], v[80:83]
	v_mfma_f32_16x16x32_bf16 v[80:83], v[202:205], v[218:221], v[80:83]
	v_mfma_f32_16x16x32_bf16 v[64:67], v[198:201], v[222:225], v[64:67]
	v_mfma_f32_16x16x32_bf16 v[64:67], v[202:205], v[226:229], v[64:67]
	v_mfma_f32_16x16x32_bf16 v[48:51], v[198:201], v[230:233], v[48:51]
	v_mfma_f32_16x16x32_bf16 v[48:51], v[202:205], v[234:237], v[48:51]
	v_mfma_f32_16x16x32_bf16 v[36:39], v[198:201], v[244:247], v[36:39]
	v_mfma_f32_16x16x32_bf16 v[36:39], v[202:205], v[248:251], v[36:39]
	v_mfma_f32_16x16x32_bf16 v[72:75], v[206:209], v[214:217], v[72:75]
	v_mfma_f32_16x16x32_bf16 v[72:75], v[210:213], v[218:221], v[72:75]
	v_mfma_f32_16x16x32_bf16 v[56:59], v[206:209], v[222:225], v[56:59]
	v_mfma_f32_16x16x32_bf16 v[56:59], v[210:213], v[226:229], v[56:59]
	v_mfma_f32_16x16x32_bf16 v[40:43], v[206:209], v[230:233], v[40:43]
	v_mfma_f32_16x16x32_bf16 v[40:43], v[210:213], v[234:237], v[40:43]
	v_mfma_f32_16x16x32_bf16 v[32:35], v[206:209], v[244:247], v[32:35]
	v_mfma_f32_16x16x32_bf16 v[32:35], v[210:213], v[248:251], v[32:35]
	s_barrier
	s_add_i32 s56, 0, 0x18000
	v_add_u32_e32 v184, s56, v174
	s_add_i32 s57, 0, 0x1c000
	ds_read_b128 v[176:179], v184
	ds_read_b128 v[180:183], v184 offset:1024
	ds_read_b128 v[190:193], v184 offset:2048
	ds_read_b128 v[194:197], v184 offset:3072
	v_add_u32_e32 v184, s57, v174
	ds_read_b128 v[198:201], v184
	ds_read_b128 v[202:205], v184 offset:1024
	ds_read_b128 v[206:209], v184 offset:2048
	ds_read_b128 v[210:213], v184 offset:3072
	s_add_u32 s30, s30, 0x80000
	s_addc_u32 s31, s31, 0
	s_mov_b32 m0, s40
	v_lshl_add_u64 v[252:253], s[30:31], 0, v[166:167]
	ds_read_b128 v[214:217], v175 offset:32768
	ds_read_b128 v[218:221], v175 offset:33792
	ds_read_b128 v[222:225], v175 offset:34816
	ds_read_b128 v[226:229], v175 offset:35840
	ds_read_b128 v[230:233], v175 offset:36864
	ds_read_b128 v[234:237], v175 offset:37888
	ds_read_b128 v[244:247], v175 offset:38912
	ds_read_b128 v[248:251], v175 offset:39936
	global_load_lds_dwordx4 v[252:253], off
	v_lshl_add_u64 v[252:253], s[30:31], 0, v[162:163]
	s_mov_b32 m0, s41
	s_nop 0
	global_load_lds_dwordx4 v[252:253], off
	s_waitcnt vmcnt(8)
	s_waitcnt lgkmcnt(0)
	s_barrier
	s_waitcnt lgkmcnt(0)
	v_mfma_f32_16x16x32_bf16 v[156:159], v[176:179], v[214:217], v[156:159]
	v_mfma_f32_16x16x32_bf16 v[156:159], v[180:183], v[218:221], v[156:159]
	v_mfma_f32_16x16x32_bf16 v[148:151], v[176:179], v[222:225], v[148:151]
	v_mfma_f32_16x16x32_bf16 v[148:151], v[180:183], v[226:229], v[148:151]
	v_mfma_f32_16x16x32_bf16 v[132:135], v[176:179], v[230:233], v[132:135]
	v_mfma_f32_16x16x32_bf16 v[132:135], v[180:183], v[234:237], v[132:135]
	v_mfma_f32_16x16x32_bf16 v[116:119], v[176:179], v[244:247], v[116:119]
	v_mfma_f32_16x16x32_bf16 v[116:119], v[180:183], v[248:251], v[116:119]
	v_mfma_f32_16x16x32_bf16 v[152:155], v[190:193], v[214:217], v[152:155]
	v_mfma_f32_16x16x32_bf16 v[152:155], v[194:197], v[218:221], v[152:155]
	v_mfma_f32_16x16x32_bf16 v[140:143], v[190:193], v[222:225], v[140:143]
	v_mfma_f32_16x16x32_bf16 v[140:143], v[194:197], v[226:229], v[140:143]
	v_mfma_f32_16x16x32_bf16 v[124:127], v[190:193], v[230:233], v[124:127]
	v_mfma_f32_16x16x32_bf16 v[124:127], v[194:197], v[234:237], v[124:127]
	v_mfma_f32_16x16x32_bf16 v[108:111], v[190:193], v[244:247], v[108:111]
	v_mfma_f32_16x16x32_bf16 v[108:111], v[194:197], v[248:251], v[108:111]
	v_mfma_f32_16x16x32_bf16 v[144:147], v[198:201], v[214:217], v[144:147]
	v_mfma_f32_16x16x32_bf16 v[144:147], v[202:205], v[218:221], v[144:147]
	v_mfma_f32_16x16x32_bf16 v[128:131], v[198:201], v[222:225], v[128:131]
	v_mfma_f32_16x16x32_bf16 v[128:131], v[202:205], v[226:229], v[128:131]
	v_mfma_f32_16x16x32_bf16 v[112:115], v[198:201], v[230:233], v[112:115]
	v_mfma_f32_16x16x32_bf16 v[112:115], v[202:205], v[234:237], v[112:115]
	v_mfma_f32_16x16x32_bf16 v[100:103], v[198:201], v[244:247], v[100:103]
	v_mfma_f32_16x16x32_bf16 v[100:103], v[202:205], v[248:251], v[100:103]
	v_mfma_f32_16x16x32_bf16 v[136:139], v[206:209], v[214:217], v[136:139]
	v_mfma_f32_16x16x32_bf16 v[136:139], v[210:213], v[218:221], v[136:139]
	v_mfma_f32_16x16x32_bf16 v[120:123], v[206:209], v[222:225], v[120:123]
	v_mfma_f32_16x16x32_bf16 v[120:123], v[210:213], v[226:229], v[120:123]
	v_mfma_f32_16x16x32_bf16 v[104:107], v[206:209], v[230:233], v[104:107]
	v_mfma_f32_16x16x32_bf16 v[104:107], v[210:213], v[234:237], v[104:107]
	v_mfma_f32_16x16x32_bf16 v[96:99], v[206:209], v[244:247], v[96:99]
	v_mfma_f32_16x16x32_bf16 v[96:99], v[210:213], v[248:251], v[96:99]
	s_barrier
	s_add_i32 s30, s56, s89
	v_lshl_add_u64 v[172:173], v[172:173], 0, s[96:97]
	s_mov_b32 m0, s30
	ds_read_b128 v[214:217], v175 offset:49152
	ds_read_b128 v[218:221], v175 offset:50176
	ds_read_b128 v[222:225], v175 offset:51200
	ds_read_b128 v[226:229], v175 offset:52224
	ds_read_b128 v[230:233], v175 offset:53248
	ds_read_b128 v[234:237], v175 offset:54272
	ds_read_b128 v[244:247], v175 offset:55296
	ds_read_b128 v[248:251], v175 offset:56320
	global_load_lds_dwordx4 v[172:173], off
	s_add_i32 m0, s30, 0x2000
	s_add_u32 s18, s18, 0x80080
	v_lshl_add_u64 v[172:173], v[186:187], 0, s[96:97]
	s_addc_u32 s19, s19, 0
	s_add_i32 s30, s57, s89
	global_load_lds_dwordx4 v[172:173], off
	v_lshl_add_u64 v[172:173], s[18:19], 0, v[164:165]
	s_mov_b32 m0, s30
	s_nop 0
	global_load_lds_dwordx4 v[172:173], off
	v_lshl_add_u64 v[172:173], s[18:19], 0, v[160:161]
	s_add_i32 m0, s30, 0x2000
	s_nop 0
	global_load_lds_dwordx4 v[172:173], off
	v_lshl_add_u64 v[172:173], v[188:189], 0, s[96:97]
	s_mov_b32 m0, s42
	s_nop 0
	global_load_lds_dwordx4 v[172:173], off
	v_lshl_add_u64 v[172:173], v[238:239], 0, s[96:97]
	s_mov_b32 m0, s43
	s_nop 0
	global_load_lds_dwordx4 v[172:173], off
	s_waitcnt vmcnt(8)
	s_waitcnt lgkmcnt(0)
	s_barrier
	s_waitcnt lgkmcnt(0)
	v_mfma_f32_16x16x32_bf16 v[92:95], v[176:179], v[214:217], v[92:95]
	v_mfma_f32_16x16x32_bf16 v[92:95], v[180:183], v[218:221], v[92:95]
	v_mfma_f32_16x16x32_bf16 v[84:87], v[176:179], v[222:225], v[84:87]
	v_mfma_f32_16x16x32_bf16 v[84:87], v[180:183], v[226:229], v[84:87]
	v_mfma_f32_16x16x32_bf16 v[68:71], v[176:179], v[230:233], v[68:71]
	v_mfma_f32_16x16x32_bf16 v[68:71], v[180:183], v[234:237], v[68:71]
	v_mfma_f32_16x16x32_bf16 v[52:55], v[176:179], v[244:247], v[52:55]
	v_mfma_f32_16x16x32_bf16 v[52:55], v[180:183], v[248:251], v[52:55]
	v_mfma_f32_16x16x32_bf16 v[88:91], v[190:193], v[214:217], v[88:91]
	v_mfma_f32_16x16x32_bf16 v[88:91], v[194:197], v[218:221], v[88:91]
	v_mfma_f32_16x16x32_bf16 v[76:79], v[190:193], v[222:225], v[76:79]
	v_mfma_f32_16x16x32_bf16 v[76:79], v[194:197], v[226:229], v[76:79]
	v_mfma_f32_16x16x32_bf16 v[60:63], v[190:193], v[230:233], v[60:63]
	v_mfma_f32_16x16x32_bf16 v[60:63], v[194:197], v[234:237], v[60:63]
	v_mfma_f32_16x16x32_bf16 v[44:47], v[190:193], v[244:247], v[44:47]
	v_mfma_f32_16x16x32_bf16 v[44:47], v[194:197], v[248:251], v[44:47]
	v_mfma_f32_16x16x32_bf16 v[80:83], v[198:201], v[214:217], v[80:83]
	v_mfma_f32_16x16x32_bf16 v[80:83], v[202:205], v[218:221], v[80:83]
	v_mfma_f32_16x16x32_bf16 v[64:67], v[198:201], v[222:225], v[64:67]
	v_mfma_f32_16x16x32_bf16 v[64:67], v[202:205], v[226:229], v[64:67]
	v_mfma_f32_16x16x32_bf16 v[48:51], v[198:201], v[230:233], v[48:51]
	v_mfma_f32_16x16x32_bf16 v[48:51], v[202:205], v[234:237], v[48:51]
	v_mfma_f32_16x16x32_bf16 v[36:39], v[198:201], v[244:247], v[36:39]
	v_mfma_f32_16x16x32_bf16 v[36:39], v[202:205], v[248:251], v[36:39]
	v_mfma_f32_16x16x32_bf16 v[72:75], v[206:209], v[214:217], v[72:75]
	v_mfma_f32_16x16x32_bf16 v[72:75], v[210:213], v[218:221], v[72:75]
	v_mfma_f32_16x16x32_bf16 v[56:59], v[206:209], v[222:225], v[56:59]
	v_mfma_f32_16x16x32_bf16 v[56:59], v[210:213], v[226:229], v[56:59]
	v_mfma_f32_16x16x32_bf16 v[40:43], v[206:209], v[230:233], v[40:43]
	v_mfma_f32_16x16x32_bf16 v[40:43], v[210:213], v[234:237], v[40:43]
	v_mfma_f32_16x16x32_bf16 v[32:35], v[206:209], v[244:247], v[32:35]
	v_mfma_f32_16x16x32_bf16 v[32:35], v[210:213], v[248:251], v[32:35]
	s_barrier
	s_add_i32 s51, s51, 2
	s_add_u32 s6, s6, 0x100
	s_addc_u32 s7, s7, 0
	s_add_u32 s49, s49, 0x100
	s_addc_u32 s50, s50, 0
	s_cmp_gt_u32 s51, 29
	s_cbranch_scc0 .LBB0_244
	s_and_b64 vcc, exec, s[86:87]
	s_cbranch_vccz .LBB0_247
	s_barrier

.LBB0_278:
	s_add_u32 s12, s10, 0x100
	s_addc_u32 s13, s11, 0
	s_add_i32 s39, 0, 0x10000
	s_cmpk_eq_i32 s31, 0x5c
	s_cselect_b32 s17, s7, s13
	s_cselect_b32 s16, s6, s12
	s_cselect_b32 s15, s9, s30
	s_cselect_b32 s14, s8, s19
	s_add_i32 s50, 0, 0x14000
	v_add_u32_e32 v150, s39, v156
	v_add_u32_e32 v154, s50, v156
	ds_read_b128 v[128:131], v150
	ds_read_b128 v[132:135], v150 offset:1024
	ds_read_b128 v[146:149], v150 offset:2048
	ds_read_b128 v[150:153], v150 offset:3072
	ds_read_b128 v[158:161], v154
	ds_read_b128 v[162:165], v154 offset:1024
	ds_read_b128 v[166:169], v154 offset:2048
	ds_read_b128 v[170:173], v154 offset:3072
	v_lshl_add_u64 v[154:155], s[10:11], 0, v[142:143]
	s_add_i32 m0, s41, 0xc000
	ds_read_b128 v[174:177], v157
	ds_read_b128 v[178:181], v157 offset:1024
	ds_read_b128 v[190:193], v157 offset:2048
	ds_read_b128 v[194:197], v157 offset:3072
	ds_read_b128 v[198:201], v157 offset:4096
	ds_read_b128 v[202:205], v157 offset:5120
	ds_read_b128 v[206:209], v157 offset:6144
	ds_read_b128 v[210:213], v157 offset:7168
	global_load_lds_dwordx4 v[154:155], off
	v_lshl_add_u64 v[154:155], s[10:11], 0, v[144:145]
	s_add_i32 m0, s41, 0xe000
	s_nop 0
	global_load_lds_dwordx4 v[154:155], off
	s_waitcnt vmcnt(8)
	s_waitcnt lgkmcnt(0)
	s_barrier
	s_waitcnt lgkmcnt(0)
	v_mfma_f32_16x16x32_bf16 v[124:127], v[128:131], v[174:177], v[124:127]
	v_mfma_f32_16x16x32_bf16 v[124:127], v[132:135], v[178:181], v[124:127]
	v_mfma_f32_16x16x32_bf16 v[108:111], v[128:131], v[190:193], v[108:111]
	v_mfma_f32_16x16x32_bf16 v[108:111], v[132:135], v[194:197], v[108:111]
	v_mfma_f32_16x16x32_bf16 v[92:95], v[128:131], v[198:201], v[92:95]
	v_mfma_f32_16x16x32_bf16 v[92:95], v[132:135], v[202:205], v[92:95]
	v_mfma_f32_16x16x32_bf16 v[76:79], v[128:131], v[206:209], v[76:79]
	v_mfma_f32_16x16x32_bf16 v[76:79], v[132:135], v[210:213], v[76:79]
	v_mfma_f32_16x16x32_bf16 v[120:123], v[146:149], v[174:177], v[120:123]
	v_mfma_f32_16x16x32_bf16 v[120:123], v[150:153], v[178:181], v[120:123]
	v_mfma_f32_16x16x32_bf16 v[104:107], v[146:149], v[190:193], v[104:107]
	v_mfma_f32_16x16x32_bf16 v[104:107], v[150:153], v[194:197], v[104:107]
	v_mfma_f32_16x16x32_bf16 v[88:91], v[146:149], v[198:201], v[88:91]
	v_mfma_f32_16x16x32_bf16 v[88:91], v[150:153], v[202:205], v[88:91]
	v_mfma_f32_16x16x32_bf16 v[72:75], v[146:149], v[206:209], v[72:75]
	v_mfma_f32_16x16x32_bf16 v[72:75], v[150:153], v[210:213], v[72:75]
	v_mfma_f32_16x16x32_bf16 v[116:119], v[158:161], v[174:177], v[116:119]
	v_mfma_f32_16x16x32_bf16 v[116:119], v[162:165], v[178:181], v[116:119]
	v_mfma_f32_16x16x32_bf16 v[100:103], v[158:161], v[190:193], v[100:103]
	v_mfma_f32_16x16x32_bf16 v[100:103], v[162:165], v[194:197], v[100:103]
	v_mfma_f32_16x16x32_bf16 v[84:87], v[158:161], v[198:201], v[84:87]
	v_mfma_f32_16x16x32_bf16 v[84:87], v[162:165], v[202:205], v[84:87]
	v_mfma_f32_16x16x32_bf16 v[68:71], v[158:161], v[206:209], v[68:71]
	v_mfma_f32_16x16x32_bf16 v[68:71], v[162:165], v[210:213], v[68:71]
	v_mfma_f32_16x16x32_bf16 v[112:115], v[166:169], v[174:177], v[112:115]
	v_mfma_f32_16x16x32_bf16 v[112:115], v[170:173], v[178:181], v[112:115]
	v_mfma_f32_16x16x32_bf16 v[96:99], v[166:169], v[190:193], v[96:99]
	v_mfma_f32_16x16x32_bf16 v[96:99], v[170:173], v[194:197], v[96:99]
	v_mfma_f32_16x16x32_bf16 v[80:83], v[166:169], v[198:201], v[80:83]
	v_mfma_f32_16x16x32_bf16 v[80:83], v[170:173], v[202:205], v[80:83]
	v_mfma_f32_16x16x32_bf16 v[64:67], v[166:169], v[206:209], v[64:67]
	v_mfma_f32_16x16x32_bf16 v[64:67], v[170:173], v[210:213], v[64:67]
	s_barrier
	s_add_i32 s10, s39, s89
	v_lshl_add_u64 v[154:155], s[14:15], 0, v[184:185]
	s_mov_b32 m0, s10
	ds_read_b128 v[174:177], v157 offset:16384
	ds_read_b128 v[178:181], v157 offset:17408
	ds_read_b128 v[190:193], v157 offset:18432
	ds_read_b128 v[194:197], v157 offset:19456
	ds_read_b128 v[198:201], v157 offset:20480
	ds_read_b128 v[202:205], v157 offset:21504
	ds_read_b128 v[206:209], v157 offset:22528
	ds_read_b128 v[210:213], v157 offset:23552
	global_load_lds_dwordx4 v[154:155], off
	s_add_i32 m0, s10, 0x2000
	s_add_u32 s10, s14, 0x180000
	v_lshl_add_u64 v[182:183], s[14:15], 0, v[140:141]
	s_addc_u32 s11, s15, 0
	s_add_i32 s39, s50, s89
	global_load_lds_dwordx4 v[182:183], off
	v_lshl_add_u64 v[186:187], s[10:11], 0, v[184:185]
	s_mov_b32 m0, s39
	v_lshl_add_u64 v[188:189], s[16:17], 0, v[138:139]
	global_load_lds_dwordx4 v[186:187], off
	v_lshl_add_u64 v[186:187], s[10:11], 0, v[140:141]
	s_add_i32 m0, s39, 0x2000
	s_nop 0
	global_load_lds_dwordx4 v[186:187], off
	v_lshl_add_u64 v[186:187], s[16:17], 0, v[136:137]
	s_mov_b32 m0, s41
	s_nop 0
	global_load_lds_dwordx4 v[186:187], off
	s_mov_b32 m0, s42
	s_nop 0
	global_load_lds_dwordx4 v[188:189], off
	s_waitcnt vmcnt(8)
	s_waitcnt lgkmcnt(0)
	s_barrier
	s_waitcnt lgkmcnt(0)
	v_mfma_f32_16x16x32_bf16 v[60:63], v[128:131], v[174:177], v[60:63]
	v_mfma_f32_16x16x32_bf16 v[60:63], v[132:135], v[178:181], v[60:63]
	v_mfma_f32_16x16x32_bf16 v[44:47], v[128:131], v[190:193], v[44:47]
	v_mfma_f32_16x16x32_bf16 v[44:47], v[132:135], v[194:197], v[44:47]
	v_mfma_f32_16x16x32_bf16 v[28:31], v[128:131], v[198:201], v[28:31]
	v_mfma_f32_16x16x32_bf16 v[28:31], v[132:135], v[202:205], v[28:31]
	v_mfma_f32_16x16x32_bf16 v[12:15], v[128:131], v[206:209], v[12:15]
	v_mfma_f32_16x16x32_bf16 v[12:15], v[132:135], v[210:213], v[12:15]
	v_mfma_f32_16x16x32_bf16 v[56:59], v[146:149], v[174:177], v[56:59]
	v_mfma_f32_16x16x32_bf16 v[56:59], v[150:153], v[178:181], v[56:59]
	v_mfma_f32_16x16x32_bf16 v[40:43], v[146:149], v[190:193], v[40:43]
	v_mfma_f32_16x16x32_bf16 v[40:43], v[150:153], v[194:197], v[40:43]
	v_mfma_f32_16x16x32_bf16 v[24:27], v[146:149], v[198:201], v[24:27]
	v_mfma_f32_16x16x32_bf16 v[24:27], v[150:153], v[202:205], v[24:27]
	v_mfma_f32_16x16x32_bf16 v[8:11], v[146:149], v[206:209], v[8:11]
	v_mfma_f32_16x16x32_bf16 v[8:11], v[150:153], v[210:213], v[8:11]
	v_mfma_f32_16x16x32_bf16 v[52:55], v[158:161], v[174:177], v[52:55]
	v_mfma_f32_16x16x32_bf16 v[52:55], v[162:165], v[178:181], v[52:55]
	v_mfma_f32_16x16x32_bf16 v[36:39], v[158:161], v[190:193], v[36:39]
	v_mfma_f32_16x16x32_bf16 v[36:39], v[162:165], v[194:197], v[36:39]
	v_mfma_f32_16x16x32_bf16 v[20:23], v[158:161], v[198:201], v[20:23]
	v_mfma_f32_16x16x32_bf16 v[20:23], v[162:165], v[202:205], v[20:23]
	v_mfma_f32_16x16x32_bf16 v[4:7], v[158:161], v[206:209], v[4:7]
	v_mfma_f32_16x16x32_bf16 v[4:7], v[162:165], v[210:213], v[4:7]
	v_mfma_f32_16x16x32_bf16 v[48:51], v[166:169], v[174:177], v[48:51]
	v_mfma_f32_16x16x32_bf16 v[48:51], v[170:173], v[178:181], v[48:51]
	v_mfma_f32_16x16x32_bf16 v[32:35], v[166:169], v[190:193], v[32:35]
	v_mfma_f32_16x16x32_bf16 v[32:35], v[170:173], v[194:197], v[32:35]
	v_mfma_f32_16x16x32_bf16 v[16:19], v[166:169], v[198:201], v[16:19]
	v_mfma_f32_16x16x32_bf16 v[16:19], v[170:173], v[202:205], v[16:19]
	v_mfma_f32_16x16x32_bf16 v[0:3], v[166:169], v[206:209], v[0:3]
	v_mfma_f32_16x16x32_bf16 v[0:3], v[170:173], v[210:213], v[0:3]
	s_barrier
	s_add_i32 s39, 0, 0x18000
	s_add_i32 s50, 0, 0x1c000
	v_add_u32_e32 v150, s39, v156
	v_add_u32_e32 v170, s50, v156
	ds_read_b128 v[128:131], v150
	ds_read_b128 v[132:135], v150 offset:1024
	ds_read_b128 v[146:149], v150 offset:2048
	ds_read_b128 v[150:153], v150 offset:3072
	ds_read_b128 v[158:161], v170
	ds_read_b128 v[162:165], v170 offset:1024
	ds_read_b128 v[166:169], v170 offset:2048
	ds_read_b128 v[170:173], v170 offset:3072
	s_add_u32 s10, s16, 0x180000
	s_addc_u32 s11, s17, 0
	s_mov_b32 m0, s43
	v_lshl_add_u64 v[214:215], s[10:11], 0, v[136:137]
	ds_read_b128 v[174:177], v157 offset:32768
	ds_read_b128 v[178:181], v157 offset:33792
	ds_read_b128 v[190:193], v157 offset:34816
	ds_read_b128 v[194:197], v157 offset:35840
	ds_read_b128 v[198:201], v157 offset:36864
	ds_read_b128 v[202:205], v157 offset:37888
	ds_read_b128 v[206:209], v157 offset:38912
	ds_read_b128 v[210:213], v157 offset:39936
	global_load_lds_dwordx4 v[214:215], off
	v_lshl_add_u64 v[214:215], s[10:11], 0, v[138:139]
	s_mov_b32 m0, s44
	s_nop 0
	global_load_lds_dwordx4 v[214:215], off
	s_waitcnt vmcnt(8)
	s_waitcnt lgkmcnt(0)
	s_barrier
	s_waitcnt lgkmcnt(0)
	v_mfma_f32_16x16x32_bf16 v[124:127], v[128:131], v[174:177], v[124:127]
	v_mfma_f32_16x16x32_bf16 v[124:127], v[132:135], v[178:181], v[124:127]
	v_mfma_f32_16x16x32_bf16 v[108:111], v[128:131], v[190:193], v[108:111]
	v_mfma_f32_16x16x32_bf16 v[108:111], v[132:135], v[194:197], v[108:111]
	v_mfma_f32_16x16x32_bf16 v[92:95], v[128:131], v[198:201], v[92:95]
	v_mfma_f32_16x16x32_bf16 v[92:95], v[132:135], v[202:205], v[92:95]
	v_mfma_f32_16x16x32_bf16 v[76:79], v[128:131], v[206:209], v[76:79]
	v_mfma_f32_16x16x32_bf16 v[76:79], v[132:135], v[210:213], v[76:79]
	v_mfma_f32_16x16x32_bf16 v[120:123], v[146:149], v[174:177], v[120:123]
	v_mfma_f32_16x16x32_bf16 v[120:123], v[150:153], v[178:181], v[120:123]
	v_mfma_f32_16x16x32_bf16 v[104:107], v[146:149], v[190:193], v[104:107]
	v_mfma_f32_16x16x32_bf16 v[104:107], v[150:153], v[194:197], v[104:107]
	v_mfma_f32_16x16x32_bf16 v[88:91], v[146:149], v[198:201], v[88:91]
	v_mfma_f32_16x16x32_bf16 v[88:91], v[150:153], v[202:205], v[88:91]
	v_mfma_f32_16x16x32_bf16 v[72:75], v[146:149], v[206:209], v[72:75]
	v_mfma_f32_16x16x32_bf16 v[72:75], v[150:153], v[210:213], v[72:75]
	v_mfma_f32_16x16x32_bf16 v[116:119], v[158:161], v[174:177], v[116:119]
	v_mfma_f32_16x16x32_bf16 v[116:119], v[162:165], v[178:181], v[116:119]
	v_mfma_f32_16x16x32_bf16 v[100:103], v[158:161], v[190:193], v[100:103]
	v_mfma_f32_16x16x32_bf16 v[100:103], v[162:165], v[194:197], v[100:103]
	v_mfma_f32_16x16x32_bf16 v[84:87], v[158:161], v[198:201], v[84:87]
	v_mfma_f32_16x16x32_bf16 v[84:87], v[162:165], v[202:205], v[84:87]
	v_mfma_f32_16x16x32_bf16 v[68:71], v[158:161], v[206:209], v[68:71]
	v_mfma_f32_16x16x32_bf16 v[68:71], v[162:165], v[210:213], v[68:71]
	v_mfma_f32_16x16x32_bf16 v[112:115], v[166:169], v[174:177], v[112:115]
	v_mfma_f32_16x16x32_bf16 v[112:115], v[170:173], v[178:181], v[112:115]
	v_mfma_f32_16x16x32_bf16 v[96:99], v[166:169], v[190:193], v[96:99]
	v_mfma_f32_16x16x32_bf16 v[96:99], v[170:173], v[194:197], v[96:99]
	v_mfma_f32_16x16x32_bf16 v[80:83], v[166:169], v[198:201], v[80:83]
	v_mfma_f32_16x16x32_bf16 v[80:83], v[170:173], v[202:205], v[80:83]
	v_mfma_f32_16x16x32_bf16 v[64:67], v[166:169], v[206:209], v[64:67]
	v_mfma_f32_16x16x32_bf16 v[64:67], v[170:173], v[210:213], v[64:67]
	s_barrier
	s_add_i32 s10, s39, s89
	v_lshl_add_u64 v[154:155], v[154:155], 0, s[96:97]
	s_mov_b32 m0, s10
	ds_read_b128 v[174:177], v157 offset:49152
	ds_read_b128 v[178:181], v157 offset:50176
	ds_read_b128 v[190:193], v157 offset:51200
	ds_read_b128 v[194:197], v157 offset:52224
	ds_read_b128 v[198:201], v157 offset:53248
	ds_read_b128 v[202:205], v157 offset:54272
	ds_read_b128 v[206:209], v157 offset:55296
	ds_read_b128 v[210:213], v157 offset:56320
	global_load_lds_dwordx4 v[154:155], off
	s_add_i32 m0, s10, 0x2000
	s_add_u32 s10, s14, 0x180080
	v_lshl_add_u64 v[154:155], v[182:183], 0, s[96:97]
	s_addc_u32 s11, s15, 0
	s_add_i32 s14, s50, s89
	global_load_lds_dwordx4 v[154:155], off
	v_lshl_add_u64 v[154:155], s[10:11], 0, v[184:185]
	s_mov_b32 m0, s14
	s_nop 0
	global_load_lds_dwordx4 v[154:155], off
	v_lshl_add_u64 v[154:155], s[10:11], 0, v[140:141]
	s_add_i32 m0, s14, 0x2000
	s_nop 0
	global_load_lds_dwordx4 v[154:155], off
	v_lshl_add_u64 v[154:155], v[186:187], 0, s[96:97]
	s_mov_b32 m0, s45
	s_nop 0
	global_load_lds_dwordx4 v[154:155], off
	v_lshl_add_u64 v[154:155], v[188:189], 0, s[96:97]
	s_mov_b32 m0, s46
	s_nop 0
	global_load_lds_dwordx4 v[154:155], off
	s_waitcnt vmcnt(8)
	s_waitcnt lgkmcnt(0)
	s_barrier
	s_waitcnt lgkmcnt(0)
	v_mfma_f32_16x16x32_bf16 v[60:63], v[128:131], v[174:177], v[60:63]
	v_mfma_f32_16x16x32_bf16 v[60:63], v[132:135], v[178:181], v[60:63]
	v_mfma_f32_16x16x32_bf16 v[44:47], v[128:131], v[190:193], v[44:47]
	v_mfma_f32_16x16x32_bf16 v[44:47], v[132:135], v[194:197], v[44:47]
	v_mfma_f32_16x16x32_bf16 v[28:31], v[128:131], v[198:201], v[28:31]
	v_mfma_f32_16x16x32_bf16 v[28:31], v[132:135], v[202:205], v[28:31]
	v_mfma_f32_16x16x32_bf16 v[12:15], v[128:131], v[206:209], v[12:15]
	v_mfma_f32_16x16x32_bf16 v[12:15], v[132:135], v[210:213], v[12:15]
	v_mfma_f32_16x16x32_bf16 v[56:59], v[146:149], v[174:177], v[56:59]
	v_mfma_f32_16x16x32_bf16 v[56:59], v[150:153], v[178:181], v[56:59]
	v_mfma_f32_16x16x32_bf16 v[40:43], v[146:149], v[190:193], v[40:43]
	v_mfma_f32_16x16x32_bf16 v[40:43], v[150:153], v[194:197], v[40:43]
	v_mfma_f32_16x16x32_bf16 v[24:27], v[146:149], v[198:201], v[24:27]
	v_mfma_f32_16x16x32_bf16 v[24:27], v[150:153], v[202:205], v[24:27]
	v_mfma_f32_16x16x32_bf16 v[8:11], v[146:149], v[206:209], v[8:11]
	v_mfma_f32_16x16x32_bf16 v[8:11], v[150:153], v[210:213], v[8:11]
	v_mfma_f32_16x16x32_bf16 v[52:55], v[158:161], v[174:177], v[52:55]
	v_mfma_f32_16x16x32_bf16 v[52:55], v[162:165], v[178:181], v[52:55]
	v_mfma_f32_16x16x32_bf16 v[36:39], v[158:161], v[190:193], v[36:39]
	v_mfma_f32_16x16x32_bf16 v[36:39], v[162:165], v[194:197], v[36:39]
	v_mfma_f32_16x16x32_bf16 v[20:23], v[158:161], v[198:201], v[20:23]
	v_mfma_f32_16x16x32_bf16 v[20:23], v[162:165], v[202:205], v[20:23]
	v_mfma_f32_16x16x32_bf16 v[4:7], v[158:161], v[206:209], v[4:7]
	v_mfma_f32_16x16x32_bf16 v[4:7], v[162:165], v[210:213], v[4:7]
	v_mfma_f32_16x16x32_bf16 v[48:51], v[166:169], v[174:177], v[48:51]
	v_mfma_f32_16x16x32_bf16 v[48:51], v[170:173], v[178:181], v[48:51]
	v_mfma_f32_16x16x32_bf16 v[32:35], v[166:169], v[190:193], v[32:35]
	v_mfma_f32_16x16x32_bf16 v[32:35], v[170:173], v[194:197], v[32:35]
	v_mfma_f32_16x16x32_bf16 v[16:19], v[166:169], v[198:201], v[16:19]
	v_mfma_f32_16x16x32_bf16 v[16:19], v[170:173], v[202:205], v[16:19]
	v_mfma_f32_16x16x32_bf16 v[0:3], v[166:169], v[206:209], v[0:3]
	v_mfma_f32_16x16x32_bf16 v[0:3], v[170:173], v[210:213], v[0:3]
	s_barrier
	s_add_i32 s31, s31, 2
	s_add_u32 s19, s19, 0x100
	s_addc_u32 s30, s30, 0
	s_cmpk_gt_u32 s31, 0x5d
	s_mov_b64 s[10:11], s[12:13]
	s_cbranch_scc0 .LBB0_278
	s_and_b64 vcc, exec, s[86:87]
	s_cbranch_vccz .LBB0_281
	s_barrier

.LBB0_409:
	s_add_u32 s18, s6, 0xfff80080
	s_addc_u32 s19, s7, -1
	s_add_i32 s49, 0, 0x10000
	s_cmp_eq_u32 s48, 28
	s_cselect_b32 s23, s11, s19
	s_cselect_b32 s22, s44, s18
	v_add_u32_e32 v180, s49, v182
	s_cselect_b32 s19, s9, s47
	s_cselect_b32 s18, s45, s46
	s_add_i32 s56, 0, 0x14000
	ds_read_b128 v[172:175], v180
	ds_read_b128 v[176:179], v180 offset:1024
	ds_read_b128 v[190:193], v180 offset:2048
	ds_read_b128 v[194:197], v180 offset:3072
	v_add_u32_e32 v180, s56, v182
	ds_read_b128 v[198:201], v180
	ds_read_b128 v[202:205], v180 offset:1024
	ds_read_b128 v[206:209], v180 offset:2048
	ds_read_b128 v[210:213], v180 offset:3072
	v_lshl_add_u64 v[180:181], s[6:7], 0, v[168:169]
	s_add_i32 m0, s17, 0xc000
	ds_read_b128 v[214:217], v183
	ds_read_b128 v[218:221], v183 offset:1024
	ds_read_b128 v[222:225], v183 offset:2048
	ds_read_b128 v[226:229], v183 offset:3072
	ds_read_b128 v[230:233], v183 offset:4096
	ds_read_b128 v[234:237], v183 offset:5120
	ds_read_b128 v[244:247], v183 offset:6144
	ds_read_b128 v[248:251], v183 offset:7168
	global_load_lds_dwordx4 v[180:181], off
	v_lshl_add_u64 v[180:181], s[6:7], 0, v[170:171]
	s_add_i32 m0, s17, 0xe000
	s_nop 0
	global_load_lds_dwordx4 v[180:181], off
	s_waitcnt vmcnt(8)
	s_waitcnt lgkmcnt(0)
	s_barrier
	s_waitcnt lgkmcnt(0)
	v_mfma_f32_16x16x32_bf16 v[156:159], v[172:175], v[214:217], v[156:159]
	v_mfma_f32_16x16x32_bf16 v[156:159], v[176:179], v[218:221], v[156:159]
	v_mfma_f32_16x16x32_bf16 v[140:143], v[172:175], v[222:225], v[140:143]
	v_mfma_f32_16x16x32_bf16 v[140:143], v[176:179], v[226:229], v[140:143]
	v_mfma_f32_16x16x32_bf16 v[124:127], v[172:175], v[230:233], v[124:127]
	v_mfma_f32_16x16x32_bf16 v[124:127], v[176:179], v[234:237], v[124:127]
	v_mfma_f32_16x16x32_bf16 v[108:111], v[172:175], v[244:247], v[108:111]
	v_mfma_f32_16x16x32_bf16 v[108:111], v[176:179], v[248:251], v[108:111]
	v_mfma_f32_16x16x32_bf16 v[152:155], v[190:193], v[214:217], v[152:155]
	v_mfma_f32_16x16x32_bf16 v[152:155], v[194:197], v[218:221], v[152:155]
	v_mfma_f32_16x16x32_bf16 v[136:139], v[190:193], v[222:225], v[136:139]
	v_mfma_f32_16x16x32_bf16 v[136:139], v[194:197], v[226:229], v[136:139]
	v_mfma_f32_16x16x32_bf16 v[120:123], v[190:193], v[230:233], v[120:123]
	v_mfma_f32_16x16x32_bf16 v[120:123], v[194:197], v[234:237], v[120:123]
	v_mfma_f32_16x16x32_bf16 v[104:107], v[190:193], v[244:247], v[104:107]
	v_mfma_f32_16x16x32_bf16 v[104:107], v[194:197], v[248:251], v[104:107]
	v_mfma_f32_16x16x32_bf16 v[148:151], v[198:201], v[214:217], v[148:151]
	v_mfma_f32_16x16x32_bf16 v[148:151], v[202:205], v[218:221], v[148:151]
	v_mfma_f32_16x16x32_bf16 v[132:135], v[198:201], v[222:225], v[132:135]
	v_mfma_f32_16x16x32_bf16 v[132:135], v[202:205], v[226:229], v[132:135]
	v_mfma_f32_16x16x32_bf16 v[116:119], v[198:201], v[230:233], v[116:119]
	v_mfma_f32_16x16x32_bf16 v[116:119], v[202:205], v[234:237], v[116:119]
	v_mfma_f32_16x16x32_bf16 v[100:103], v[198:201], v[244:247], v[100:103]
	v_mfma_f32_16x16x32_bf16 v[100:103], v[202:205], v[248:251], v[100:103]
	v_mfma_f32_16x16x32_bf16 v[144:147], v[206:209], v[214:217], v[144:147]
	v_mfma_f32_16x16x32_bf16 v[144:147], v[210:213], v[218:221], v[144:147]
	v_mfma_f32_16x16x32_bf16 v[128:131], v[206:209], v[222:225], v[128:131]
	v_mfma_f32_16x16x32_bf16 v[128:131], v[210:213], v[226:229], v[128:131]
	v_mfma_f32_16x16x32_bf16 v[112:115], v[206:209], v[230:233], v[112:115]
	v_mfma_f32_16x16x32_bf16 v[112:115], v[210:213], v[234:237], v[112:115]
	v_mfma_f32_16x16x32_bf16 v[96:99], v[206:209], v[244:247], v[96:99]
	v_mfma_f32_16x16x32_bf16 v[96:99], v[210:213], v[248:251], v[96:99]
	s_barrier
	s_add_i32 s49, s49, s89
	v_lshl_add_u64 v[180:181], s[18:19], 0, v[164:165]
	s_mov_b32 m0, s49
	ds_read_b128 v[214:217], v183 offset:16384
	ds_read_b128 v[218:221], v183 offset:17408
	ds_read_b128 v[222:225], v183 offset:18432
	ds_read_b128 v[226:229], v183 offset:19456
	ds_read_b128 v[230:233], v183 offset:20480
	ds_read_b128 v[234:237], v183 offset:21504
	ds_read_b128 v[244:247], v183 offset:22528
	ds_read_b128 v[248:251], v183 offset:23552
	global_load_lds_dwordx4 v[180:181], off
	s_add_i32 m0, s49, 0x2000
	s_add_u32 s50, s18, 0x80000
	v_lshl_add_u64 v[186:187], s[18:19], 0, v[160:161]
	s_addc_u32 s51, s19, 0
	s_add_i32 s49, s56, s89
	global_load_lds_dwordx4 v[186:187], off
	v_lshl_add_u64 v[188:189], s[50:51], 0, v[164:165]
	s_mov_b32 m0, s49
	v_lshl_add_u64 v[238:239], s[22:23], 0, v[162:163]
	global_load_lds_dwordx4 v[188:189], off
	v_lshl_add_u64 v[188:189], s[50:51], 0, v[160:161]
	s_add_i32 m0, s49, 0x2000
	s_nop 0
	global_load_lds_dwordx4 v[188:189], off
	v_lshl_add_u64 v[188:189], s[22:23], 0, v[166:167]
	s_mov_b32 m0, s17
	s_nop 0
	global_load_lds_dwordx4 v[188:189], off
	s_mov_b32 m0, s36
	s_nop 0
	global_load_lds_dwordx4 v[238:239], off
	s_waitcnt vmcnt(8)
	s_waitcnt lgkmcnt(0)
	s_barrier
	s_waitcnt lgkmcnt(0)
	v_mfma_f32_16x16x32_bf16 v[92:95], v[172:175], v[214:217], v[92:95]
	v_mfma_f32_16x16x32_bf16 v[92:95], v[176:179], v[218:221], v[92:95]
	v_mfma_f32_16x16x32_bf16 v[76:79], v[172:175], v[222:225], v[76:79]
	v_mfma_f32_16x16x32_bf16 v[76:79], v[176:179], v[226:229], v[76:79]
	v_mfma_f32_16x16x32_bf16 v[60:63], v[172:175], v[230:233], v[60:63]
	v_mfma_f32_16x16x32_bf16 v[60:63], v[176:179], v[234:237], v[60:63]
	v_mfma_f32_16x16x32_bf16 v[44:47], v[172:175], v[244:247], v[44:47]
	v_mfma_f32_16x16x32_bf16 v[44:47], v[176:179], v[248:251], v[44:47]
	v_mfma_f32_16x16x32_bf16 v[88:91], v[190:193], v[214:217], v[88:91]
	v_mfma_f32_16x16x32_bf16 v[88:91], v[194:197], v[218:221], v[88:91]
	v_mfma_f32_16x16x32_bf16 v[72:75], v[190:193], v[222:225], v[72:75]
	v_mfma_f32_16x16x32_bf16 v[72:75], v[194:197], v[226:229], v[72:75]
	v_mfma_f32_16x16x32_bf16 v[56:59], v[190:193], v[230:233], v[56:59]
	v_mfma_f32_16x16x32_bf16 v[56:59], v[194:197], v[234:237], v[56:59]
	v_mfma_f32_16x16x32_bf16 v[40:43], v[190:193], v[244:247], v[40:43]
	v_mfma_f32_16x16x32_bf16 v[40:43], v[194:197], v[248:251], v[40:43]
	v_mfma_f32_16x16x32_bf16 v[84:87], v[198:201], v[214:217], v[84:87]
	v_mfma_f32_16x16x32_bf16 v[84:87], v[202:205], v[218:221], v[84:87]
	v_mfma_f32_16x16x32_bf16 v[68:71], v[198:201], v[222:225], v[68:71]
	v_mfma_f32_16x16x32_bf16 v[68:71], v[202:205], v[226:229], v[68:71]
	v_mfma_f32_16x16x32_bf16 v[52:55], v[198:201], v[230:233], v[52:55]
	v_mfma_f32_16x16x32_bf16 v[52:55], v[202:205], v[234:237], v[52:55]
	v_mfma_f32_16x16x32_bf16 v[36:39], v[198:201], v[244:247], v[36:39]
	v_mfma_f32_16x16x32_bf16 v[36:39], v[202:205], v[248:251], v[36:39]
	v_mfma_f32_16x16x32_bf16 v[80:83], v[206:209], v[214:217], v[80:83]
	v_mfma_f32_16x16x32_bf16 v[80:83], v[210:213], v[218:221], v[80:83]
	v_mfma_f32_16x16x32_bf16 v[64:67], v[206:209], v[222:225], v[64:67]
	v_mfma_f32_16x16x32_bf16 v[64:67], v[210:213], v[226:229], v[64:67]
	v_mfma_f32_16x16x32_bf16 v[48:51], v[206:209], v[230:233], v[48:51]
	v_mfma_f32_16x16x32_bf16 v[48:51], v[210:213], v[234:237], v[48:51]
	v_mfma_f32_16x16x32_bf16 v[32:35], v[206:209], v[244:247], v[32:35]
	v_mfma_f32_16x16x32_bf16 v[32:35], v[210:213], v[248:251], v[32:35]
	s_barrier
	s_add_i32 s49, 0, 0x18000
	v_add_u32_e32 v184, s49, v182
	s_add_i32 s50, 0, 0x1c000
	ds_read_b128 v[172:175], v184
	ds_read_b128 v[176:179], v184 offset:1024
	ds_read_b128 v[190:193], v184 offset:2048
	ds_read_b128 v[194:197], v184 offset:3072
	v_add_u32_e32 v184, s50, v182
	ds_read_b128 v[198:201], v184
	ds_read_b128 v[202:205], v184 offset:1024
	ds_read_b128 v[206:209], v184 offset:2048
	ds_read_b128 v[210:213], v184 offset:3072
	s_add_u32 s22, s22, 0x80000
	s_addc_u32 s23, s23, 0
	s_mov_b32 m0, s37
	v_lshl_add_u64 v[252:253], s[22:23], 0, v[166:167]
	ds_read_b128 v[214:217], v183 offset:32768
	ds_read_b128 v[218:221], v183 offset:33792
	ds_read_b128 v[222:225], v183 offset:34816
	ds_read_b128 v[226:229], v183 offset:35840
	ds_read_b128 v[230:233], v183 offset:36864
	ds_read_b128 v[234:237], v183 offset:37888
	ds_read_b128 v[244:247], v183 offset:38912
	ds_read_b128 v[248:251], v183 offset:39936
	global_load_lds_dwordx4 v[252:253], off
	v_lshl_add_u64 v[252:253], s[22:23], 0, v[162:163]
	s_mov_b32 m0, s38
	s_nop 0
	global_load_lds_dwordx4 v[252:253], off
	s_waitcnt vmcnt(8)
	s_waitcnt lgkmcnt(0)
	s_barrier
	s_waitcnt lgkmcnt(0)
	v_mfma_f32_16x16x32_bf16 v[156:159], v[172:175], v[214:217], v[156:159]
	v_mfma_f32_16x16x32_bf16 v[156:159], v[176:179], v[218:221], v[156:159]
	v_mfma_f32_16x16x32_bf16 v[140:143], v[172:175], v[222:225], v[140:143]
	v_mfma_f32_16x16x32_bf16 v[140:143], v[176:179], v[226:229], v[140:143]
	v_mfma_f32_16x16x32_bf16 v[124:127], v[172:175], v[230:233], v[124:127]
	v_mfma_f32_16x16x32_bf16 v[124:127], v[176:179], v[234:237], v[124:127]
	v_mfma_f32_16x16x32_bf16 v[108:111], v[172:175], v[244:247], v[108:111]
	v_mfma_f32_16x16x32_bf16 v[108:111], v[176:179], v[248:251], v[108:111]
	v_mfma_f32_16x16x32_bf16 v[152:155], v[190:193], v[214:217], v[152:155]
	v_mfma_f32_16x16x32_bf16 v[152:155], v[194:197], v[218:221], v[152:155]
	v_mfma_f32_16x16x32_bf16 v[136:139], v[190:193], v[222:225], v[136:139]
	v_mfma_f32_16x16x32_bf16 v[136:139], v[194:197], v[226:229], v[136:139]
	v_mfma_f32_16x16x32_bf16 v[120:123], v[190:193], v[230:233], v[120:123]
	v_mfma_f32_16x16x32_bf16 v[120:123], v[194:197], v[234:237], v[120:123]
	v_mfma_f32_16x16x32_bf16 v[104:107], v[190:193], v[244:247], v[104:107]
	v_mfma_f32_16x16x32_bf16 v[104:107], v[194:197], v[248:251], v[104:107]
	v_mfma_f32_16x16x32_bf16 v[148:151], v[198:201], v[214:217], v[148:151]
	v_mfma_f32_16x16x32_bf16 v[148:151], v[202:205], v[218:221], v[148:151]
	v_mfma_f32_16x16x32_bf16 v[132:135], v[198:201], v[222:225], v[132:135]
	v_mfma_f32_16x16x32_bf16 v[132:135], v[202:205], v[226:229], v[132:135]
	v_mfma_f32_16x16x32_bf16 v[116:119], v[198:201], v[230:233], v[116:119]
	v_mfma_f32_16x16x32_bf16 v[116:119], v[202:205], v[234:237], v[116:119]
	v_mfma_f32_16x16x32_bf16 v[100:103], v[198:201], v[244:247], v[100:103]
	v_mfma_f32_16x16x32_bf16 v[100:103], v[202:205], v[248:251], v[100:103]
	v_mfma_f32_16x16x32_bf16 v[144:147], v[206:209], v[214:217], v[144:147]
	v_mfma_f32_16x16x32_bf16 v[144:147], v[210:213], v[218:221], v[144:147]
	v_mfma_f32_16x16x32_bf16 v[128:131], v[206:209], v[222:225], v[128:131]
	v_mfma_f32_16x16x32_bf16 v[128:131], v[210:213], v[226:229], v[128:131]
	v_mfma_f32_16x16x32_bf16 v[112:115], v[206:209], v[230:233], v[112:115]
	v_mfma_f32_16x16x32_bf16 v[112:115], v[210:213], v[234:237], v[112:115]
	v_mfma_f32_16x16x32_bf16 v[96:99], v[206:209], v[244:247], v[96:99]
	v_mfma_f32_16x16x32_bf16 v[96:99], v[210:213], v[248:251], v[96:99]
	s_barrier
	s_add_i32 s22, s49, s89
	v_lshl_add_u64 v[180:181], v[180:181], 0, s[96:97]
	s_mov_b32 m0, s22
	ds_read_b128 v[214:217], v183 offset:49152
	ds_read_b128 v[218:221], v183 offset:50176
	ds_read_b128 v[222:225], v183 offset:51200
	ds_read_b128 v[226:229], v183 offset:52224
	ds_read_b128 v[230:233], v183 offset:53248
	ds_read_b128 v[234:237], v183 offset:54272
	ds_read_b128 v[244:247], v183 offset:55296
	ds_read_b128 v[248:251], v183 offset:56320
	global_load_lds_dwordx4 v[180:181], off
	s_add_i32 m0, s22, 0x2000
	s_add_u32 s18, s18, 0x80080
	v_lshl_add_u64 v[180:181], v[186:187], 0, s[96:97]
	s_addc_u32 s19, s19, 0
	s_add_i32 s22, s50, s89
	global_load_lds_dwordx4 v[180:181], off
	v_lshl_add_u64 v[180:181], s[18:19], 0, v[164:165]
	s_mov_b32 m0, s22
	s_nop 0
	global_load_lds_dwordx4 v[180:181], off
	v_lshl_add_u64 v[180:181], s[18:19], 0, v[160:161]
	s_add_i32 m0, s22, 0x2000
	s_nop 0
	global_load_lds_dwordx4 v[180:181], off
	v_lshl_add_u64 v[180:181], v[188:189], 0, s[96:97]
	s_mov_b32 m0, s39
	s_nop 0
	global_load_lds_dwordx4 v[180:181], off
	v_lshl_add_u64 v[180:181], v[238:239], 0, s[96:97]
	s_mov_b32 m0, s40
	s_nop 0
	global_load_lds_dwordx4 v[180:181], off
	s_waitcnt vmcnt(8)
	s_waitcnt lgkmcnt(0)
	s_barrier
	s_waitcnt lgkmcnt(0)
	v_mfma_f32_16x16x32_bf16 v[92:95], v[172:175], v[214:217], v[92:95]
	v_mfma_f32_16x16x32_bf16 v[92:95], v[176:179], v[218:221], v[92:95]
	v_mfma_f32_16x16x32_bf16 v[76:79], v[172:175], v[222:225], v[76:79]
	v_mfma_f32_16x16x32_bf16 v[76:79], v[176:179], v[226:229], v[76:79]
	v_mfma_f32_16x16x32_bf16 v[60:63], v[172:175], v[230:233], v[60:63]
	v_mfma_f32_16x16x32_bf16 v[60:63], v[176:179], v[234:237], v[60:63]
	v_mfma_f32_16x16x32_bf16 v[44:47], v[172:175], v[244:247], v[44:47]
	v_mfma_f32_16x16x32_bf16 v[44:47], v[176:179], v[248:251], v[44:47]
	v_mfma_f32_16x16x32_bf16 v[88:91], v[190:193], v[214:217], v[88:91]
	v_mfma_f32_16x16x32_bf16 v[88:91], v[194:197], v[218:221], v[88:91]
	v_mfma_f32_16x16x32_bf16 v[72:75], v[190:193], v[222:225], v[72:75]
	v_mfma_f32_16x16x32_bf16 v[72:75], v[194:197], v[226:229], v[72:75]
	v_mfma_f32_16x16x32_bf16 v[56:59], v[190:193], v[230:233], v[56:59]
	v_mfma_f32_16x16x32_bf16 v[56:59], v[194:197], v[234:237], v[56:59]
	v_mfma_f32_16x16x32_bf16 v[40:43], v[190:193], v[244:247], v[40:43]
	v_mfma_f32_16x16x32_bf16 v[40:43], v[194:197], v[248:251], v[40:43]
	v_mfma_f32_16x16x32_bf16 v[84:87], v[198:201], v[214:217], v[84:87]
	v_mfma_f32_16x16x32_bf16 v[84:87], v[202:205], v[218:221], v[84:87]
	v_mfma_f32_16x16x32_bf16 v[68:71], v[198:201], v[222:225], v[68:71]
	v_mfma_f32_16x16x32_bf16 v[68:71], v[202:205], v[226:229], v[68:71]
	v_mfma_f32_16x16x32_bf16 v[52:55], v[198:201], v[230:233], v[52:55]
	v_mfma_f32_16x16x32_bf16 v[52:55], v[202:205], v[234:237], v[52:55]
	v_mfma_f32_16x16x32_bf16 v[36:39], v[198:201], v[244:247], v[36:39]
	v_mfma_f32_16x16x32_bf16 v[36:39], v[202:205], v[248:251], v[36:39]
	v_mfma_f32_16x16x32_bf16 v[80:83], v[206:209], v[214:217], v[80:83]
	v_mfma_f32_16x16x32_bf16 v[80:83], v[210:213], v[218:221], v[80:83]
	v_mfma_f32_16x16x32_bf16 v[64:67], v[206:209], v[222:225], v[64:67]
	v_mfma_f32_16x16x32_bf16 v[64:67], v[210:213], v[226:229], v[64:67]
	v_mfma_f32_16x16x32_bf16 v[48:51], v[206:209], v[230:233], v[48:51]
	v_mfma_f32_16x16x32_bf16 v[48:51], v[210:213], v[234:237], v[48:51]
	v_mfma_f32_16x16x32_bf16 v[32:35], v[206:209], v[244:247], v[32:35]
	v_mfma_f32_16x16x32_bf16 v[32:35], v[210:213], v[248:251], v[32:35]
	s_barrier
	s_add_i32 s48, s48, 2
	s_add_u32 s6, s6, 0x100
	s_addc_u32 s7, s7, 0
	s_add_u32 s46, s46, 0x100
	s_addc_u32 s47, s47, 0
	s_cmp_gt_u32 s48, 29
	s_cbranch_scc0 .LBB0_409
	s_and_b64 vcc, exec, s[86:87]
	s_cbranch_vccz .LBB0_412
	s_barrier

.LBB0_443:
	s_add_u32 s12, s10, 0x100
	s_addc_u32 s13, s11, 0
	s_add_i32 s31, 0, 0x10000
	s_cmpk_eq_i32 s23, 0x54
	s_cselect_b32 s17, s7, s13
	s_cselect_b32 s16, s6, s12
	s_cselect_b32 s15, s9, s22
	s_cselect_b32 s14, s8, s19
	s_add_i32 s45, 0, 0x14000
	v_add_u32_e32 v150, s31, v156
	v_add_u32_e32 v154, s45, v156
	ds_read_b128 v[128:131], v150
	ds_read_b128 v[132:135], v150 offset:1024
	ds_read_b128 v[146:149], v150 offset:2048
	ds_read_b128 v[150:153], v150 offset:3072
	ds_read_b128 v[158:161], v154
	ds_read_b128 v[162:165], v154 offset:1024
	ds_read_b128 v[166:169], v154 offset:2048
	ds_read_b128 v[170:173], v154 offset:3072
	v_lshl_add_u64 v[154:155], s[10:11], 0, v[142:143]
	s_add_i32 m0, s36, 0xc000
	ds_read_b128 v[174:177], v157
	ds_read_b128 v[178:181], v157 offset:1024
	ds_read_b128 v[190:193], v157 offset:2048
	ds_read_b128 v[194:197], v157 offset:3072
	ds_read_b128 v[198:201], v157 offset:4096
	ds_read_b128 v[202:205], v157 offset:5120
	ds_read_b128 v[206:209], v157 offset:6144
	ds_read_b128 v[210:213], v157 offset:7168
	global_load_lds_dwordx4 v[154:155], off
	v_lshl_add_u64 v[154:155], s[10:11], 0, v[144:145]
	s_add_i32 m0, s36, 0xe000
	s_nop 0
	global_load_lds_dwordx4 v[154:155], off
	s_waitcnt vmcnt(8)
	s_waitcnt lgkmcnt(0)
	s_barrier
	s_waitcnt lgkmcnt(0)
	v_mfma_f32_16x16x32_bf16 v[124:127], v[128:131], v[174:177], v[124:127]
	v_mfma_f32_16x16x32_bf16 v[124:127], v[132:135], v[178:181], v[124:127]
	v_mfma_f32_16x16x32_bf16 v[108:111], v[128:131], v[190:193], v[108:111]
	v_mfma_f32_16x16x32_bf16 v[108:111], v[132:135], v[194:197], v[108:111]
	v_mfma_f32_16x16x32_bf16 v[92:95], v[128:131], v[198:201], v[92:95]
	v_mfma_f32_16x16x32_bf16 v[92:95], v[132:135], v[202:205], v[92:95]
	v_mfma_f32_16x16x32_bf16 v[76:79], v[128:131], v[206:209], v[76:79]
	v_mfma_f32_16x16x32_bf16 v[76:79], v[132:135], v[210:213], v[76:79]
	v_mfma_f32_16x16x32_bf16 v[120:123], v[146:149], v[174:177], v[120:123]
	v_mfma_f32_16x16x32_bf16 v[120:123], v[150:153], v[178:181], v[120:123]
	v_mfma_f32_16x16x32_bf16 v[104:107], v[146:149], v[190:193], v[104:107]
	v_mfma_f32_16x16x32_bf16 v[104:107], v[150:153], v[194:197], v[104:107]
	v_mfma_f32_16x16x32_bf16 v[88:91], v[146:149], v[198:201], v[88:91]
	v_mfma_f32_16x16x32_bf16 v[88:91], v[150:153], v[202:205], v[88:91]
	v_mfma_f32_16x16x32_bf16 v[72:75], v[146:149], v[206:209], v[72:75]
	v_mfma_f32_16x16x32_bf16 v[72:75], v[150:153], v[210:213], v[72:75]
	v_mfma_f32_16x16x32_bf16 v[116:119], v[158:161], v[174:177], v[116:119]
	v_mfma_f32_16x16x32_bf16 v[116:119], v[162:165], v[178:181], v[116:119]
	v_mfma_f32_16x16x32_bf16 v[100:103], v[158:161], v[190:193], v[100:103]
	v_mfma_f32_16x16x32_bf16 v[100:103], v[162:165], v[194:197], v[100:103]
	v_mfma_f32_16x16x32_bf16 v[84:87], v[158:161], v[198:201], v[84:87]
	v_mfma_f32_16x16x32_bf16 v[84:87], v[162:165], v[202:205], v[84:87]
	v_mfma_f32_16x16x32_bf16 v[68:71], v[158:161], v[206:209], v[68:71]
	v_mfma_f32_16x16x32_bf16 v[68:71], v[162:165], v[210:213], v[68:71]
	v_mfma_f32_16x16x32_bf16 v[112:115], v[166:169], v[174:177], v[112:115]
	v_mfma_f32_16x16x32_bf16 v[112:115], v[170:173], v[178:181], v[112:115]
	v_mfma_f32_16x16x32_bf16 v[96:99], v[166:169], v[190:193], v[96:99]
	v_mfma_f32_16x16x32_bf16 v[96:99], v[170:173], v[194:197], v[96:99]
	v_mfma_f32_16x16x32_bf16 v[80:83], v[166:169], v[198:201], v[80:83]
	v_mfma_f32_16x16x32_bf16 v[80:83], v[170:173], v[202:205], v[80:83]
	v_mfma_f32_16x16x32_bf16 v[64:67], v[166:169], v[206:209], v[64:67]
	v_mfma_f32_16x16x32_bf16 v[64:67], v[170:173], v[210:213], v[64:67]
	s_barrier
	s_add_i32 s10, s31, s89
	v_lshl_add_u64 v[154:155], s[14:15], 0, v[184:185]
	s_mov_b32 m0, s10
	ds_read_b128 v[174:177], v157 offset:16384
	ds_read_b128 v[178:181], v157 offset:17408
	ds_read_b128 v[190:193], v157 offset:18432
	ds_read_b128 v[194:197], v157 offset:19456
	ds_read_b128 v[198:201], v157 offset:20480
	ds_read_b128 v[202:205], v157 offset:21504
	ds_read_b128 v[206:209], v157 offset:22528
	ds_read_b128 v[210:213], v157 offset:23552
	global_load_lds_dwordx4 v[154:155], off
	s_add_i32 m0, s10, 0x2000
	s_add_u32 s10, s14, 0x160000
	v_lshl_add_u64 v[182:183], s[14:15], 0, v[140:141]
	s_addc_u32 s11, s15, 0
	s_add_i32 s31, s45, s89
	global_load_lds_dwordx4 v[182:183], off
	v_lshl_add_u64 v[186:187], s[10:11], 0, v[184:185]
	s_mov_b32 m0, s31
	v_lshl_add_u64 v[188:189], s[16:17], 0, v[138:139]
	global_load_lds_dwordx4 v[186:187], off
	v_lshl_add_u64 v[186:187], s[10:11], 0, v[140:141]
	s_add_i32 m0, s31, 0x2000
	s_nop 0
	global_load_lds_dwordx4 v[186:187], off
	v_lshl_add_u64 v[186:187], s[16:17], 0, v[136:137]
	s_mov_b32 m0, s36
	s_nop 0
	global_load_lds_dwordx4 v[186:187], off
	s_mov_b32 m0, s37
	s_nop 0
	global_load_lds_dwordx4 v[188:189], off
	s_waitcnt vmcnt(8)
	s_waitcnt lgkmcnt(0)
	s_barrier
	s_waitcnt lgkmcnt(0)
	v_mfma_f32_16x16x32_bf16 v[60:63], v[128:131], v[174:177], v[60:63]
	v_mfma_f32_16x16x32_bf16 v[60:63], v[132:135], v[178:181], v[60:63]
	v_mfma_f32_16x16x32_bf16 v[44:47], v[128:131], v[190:193], v[44:47]
	v_mfma_f32_16x16x32_bf16 v[44:47], v[132:135], v[194:197], v[44:47]
	v_mfma_f32_16x16x32_bf16 v[28:31], v[128:131], v[198:201], v[28:31]
	v_mfma_f32_16x16x32_bf16 v[28:31], v[132:135], v[202:205], v[28:31]
	v_mfma_f32_16x16x32_bf16 v[12:15], v[128:131], v[206:209], v[12:15]
	v_mfma_f32_16x16x32_bf16 v[12:15], v[132:135], v[210:213], v[12:15]
	v_mfma_f32_16x16x32_bf16 v[56:59], v[146:149], v[174:177], v[56:59]
	v_mfma_f32_16x16x32_bf16 v[56:59], v[150:153], v[178:181], v[56:59]
	v_mfma_f32_16x16x32_bf16 v[40:43], v[146:149], v[190:193], v[40:43]
	v_mfma_f32_16x16x32_bf16 v[40:43], v[150:153], v[194:197], v[40:43]
	v_mfma_f32_16x16x32_bf16 v[24:27], v[146:149], v[198:201], v[24:27]
	v_mfma_f32_16x16x32_bf16 v[24:27], v[150:153], v[202:205], v[24:27]
	v_mfma_f32_16x16x32_bf16 v[8:11], v[146:149], v[206:209], v[8:11]
	v_mfma_f32_16x16x32_bf16 v[8:11], v[150:153], v[210:213], v[8:11]
	v_mfma_f32_16x16x32_bf16 v[52:55], v[158:161], v[174:177], v[52:55]
	v_mfma_f32_16x16x32_bf16 v[52:55], v[162:165], v[178:181], v[52:55]
	v_mfma_f32_16x16x32_bf16 v[36:39], v[158:161], v[190:193], v[36:39]
	v_mfma_f32_16x16x32_bf16 v[36:39], v[162:165], v[194:197], v[36:39]
	v_mfma_f32_16x16x32_bf16 v[20:23], v[158:161], v[198:201], v[20:23]
	v_mfma_f32_16x16x32_bf16 v[20:23], v[162:165], v[202:205], v[20:23]
	v_mfma_f32_16x16x32_bf16 v[4:7], v[158:161], v[206:209], v[4:7]
	v_mfma_f32_16x16x32_bf16 v[4:7], v[162:165], v[210:213], v[4:7]
	v_mfma_f32_16x16x32_bf16 v[48:51], v[166:169], v[174:177], v[48:51]
	v_mfma_f32_16x16x32_bf16 v[48:51], v[170:173], v[178:181], v[48:51]
	v_mfma_f32_16x16x32_bf16 v[32:35], v[166:169], v[190:193], v[32:35]
	v_mfma_f32_16x16x32_bf16 v[32:35], v[170:173], v[194:197], v[32:35]
	v_mfma_f32_16x16x32_bf16 v[16:19], v[166:169], v[198:201], v[16:19]
	v_mfma_f32_16x16x32_bf16 v[16:19], v[170:173], v[202:205], v[16:19]
	v_mfma_f32_16x16x32_bf16 v[0:3], v[166:169], v[206:209], v[0:3]
	v_mfma_f32_16x16x32_bf16 v[0:3], v[170:173], v[210:213], v[0:3]
	s_barrier
	s_add_i32 s31, 0, 0x18000
	s_add_i32 s45, 0, 0x1c000
	v_add_u32_e32 v150, s31, v156
	v_add_u32_e32 v170, s45, v156
	ds_read_b128 v[128:131], v150
	ds_read_b128 v[132:135], v150 offset:1024
	ds_read_b128 v[146:149], v150 offset:2048
	ds_read_b128 v[150:153], v150 offset:3072
	ds_read_b128 v[158:161], v170
	ds_read_b128 v[162:165], v170 offset:1024
	ds_read_b128 v[166:169], v170 offset:2048
	ds_read_b128 v[170:173], v170 offset:3072
	s_add_u32 s10, s16, 0x160000
	s_addc_u32 s11, s17, 0
	s_mov_b32 m0, s38
	v_lshl_add_u64 v[214:215], s[10:11], 0, v[136:137]
	ds_read_b128 v[174:177], v157 offset:32768
	ds_read_b128 v[178:181], v157 offset:33792
	ds_read_b128 v[190:193], v157 offset:34816
	ds_read_b128 v[194:197], v157 offset:35840
	ds_read_b128 v[198:201], v157 offset:36864
	ds_read_b128 v[202:205], v157 offset:37888
	ds_read_b128 v[206:209], v157 offset:38912
	ds_read_b128 v[210:213], v157 offset:39936
	global_load_lds_dwordx4 v[214:215], off
	v_lshl_add_u64 v[214:215], s[10:11], 0, v[138:139]
	s_mov_b32 m0, s39
	s_nop 0
	global_load_lds_dwordx4 v[214:215], off
	s_waitcnt vmcnt(8)
	s_waitcnt lgkmcnt(0)
	s_barrier
	s_waitcnt lgkmcnt(0)
	v_mfma_f32_16x16x32_bf16 v[124:127], v[128:131], v[174:177], v[124:127]
	v_mfma_f32_16x16x32_bf16 v[124:127], v[132:135], v[178:181], v[124:127]
	v_mfma_f32_16x16x32_bf16 v[108:111], v[128:131], v[190:193], v[108:111]
	v_mfma_f32_16x16x32_bf16 v[108:111], v[132:135], v[194:197], v[108:111]
	v_mfma_f32_16x16x32_bf16 v[92:95], v[128:131], v[198:201], v[92:95]
	v_mfma_f32_16x16x32_bf16 v[92:95], v[132:135], v[202:205], v[92:95]
	v_mfma_f32_16x16x32_bf16 v[76:79], v[128:131], v[206:209], v[76:79]
	v_mfma_f32_16x16x32_bf16 v[76:79], v[132:135], v[210:213], v[76:79]
	v_mfma_f32_16x16x32_bf16 v[120:123], v[146:149], v[174:177], v[120:123]
	v_mfma_f32_16x16x32_bf16 v[120:123], v[150:153], v[178:181], v[120:123]
	v_mfma_f32_16x16x32_bf16 v[104:107], v[146:149], v[190:193], v[104:107]
	v_mfma_f32_16x16x32_bf16 v[104:107], v[150:153], v[194:197], v[104:107]
	v_mfma_f32_16x16x32_bf16 v[88:91], v[146:149], v[198:201], v[88:91]
	v_mfma_f32_16x16x32_bf16 v[88:91], v[150:153], v[202:205], v[88:91]
	v_mfma_f32_16x16x32_bf16 v[72:75], v[146:149], v[206:209], v[72:75]
	v_mfma_f32_16x16x32_bf16 v[72:75], v[150:153], v[210:213], v[72:75]
	v_mfma_f32_16x16x32_bf16 v[116:119], v[158:161], v[174:177], v[116:119]
	v_mfma_f32_16x16x32_bf16 v[116:119], v[162:165], v[178:181], v[116:119]
	v_mfma_f32_16x16x32_bf16 v[100:103], v[158:161], v[190:193], v[100:103]
	v_mfma_f32_16x16x32_bf16 v[100:103], v[162:165], v[194:197], v[100:103]
	v_mfma_f32_16x16x32_bf16 v[84:87], v[158:161], v[198:201], v[84:87]
	v_mfma_f32_16x16x32_bf16 v[84:87], v[162:165], v[202:205], v[84:87]
	v_mfma_f32_16x16x32_bf16 v[68:71], v[158:161], v[206:209], v[68:71]
	v_mfma_f32_16x16x32_bf16 v[68:71], v[162:165], v[210:213], v[68:71]
	v_mfma_f32_16x16x32_bf16 v[112:115], v[166:169], v[174:177], v[112:115]
	v_mfma_f32_16x16x32_bf16 v[112:115], v[170:173], v[178:181], v[112:115]
	v_mfma_f32_16x16x32_bf16 v[96:99], v[166:169], v[190:193], v[96:99]
	v_mfma_f32_16x16x32_bf16 v[96:99], v[170:173], v[194:197], v[96:99]
	v_mfma_f32_16x16x32_bf16 v[80:83], v[166:169], v[198:201], v[80:83]
	v_mfma_f32_16x16x32_bf16 v[80:83], v[170:173], v[202:205], v[80:83]
	v_mfma_f32_16x16x32_bf16 v[64:67], v[166:169], v[206:209], v[64:67]
	v_mfma_f32_16x16x32_bf16 v[64:67], v[170:173], v[210:213], v[64:67]
	s_barrier
	s_add_i32 s10, s31, s89
	v_lshl_add_u64 v[154:155], v[154:155], 0, s[96:97]
	s_mov_b32 m0, s10
	ds_read_b128 v[174:177], v157 offset:49152
	ds_read_b128 v[178:181], v157 offset:50176
	ds_read_b128 v[190:193], v157 offset:51200
	ds_read_b128 v[194:197], v157 offset:52224
	ds_read_b128 v[198:201], v157 offset:53248
	ds_read_b128 v[202:205], v157 offset:54272
	ds_read_b128 v[206:209], v157 offset:55296
	ds_read_b128 v[210:213], v157 offset:56320
	global_load_lds_dwordx4 v[154:155], off
	s_add_i32 m0, s10, 0x2000
	s_add_u32 s10, s14, 0x160080
	v_lshl_add_u64 v[154:155], v[182:183], 0, s[96:97]
	s_addc_u32 s11, s15, 0
	s_add_i32 s14, s45, s89
	global_load_lds_dwordx4 v[154:155], off
	v_lshl_add_u64 v[154:155], s[10:11], 0, v[184:185]
	s_mov_b32 m0, s14
	s_nop 0
	global_load_lds_dwordx4 v[154:155], off
	v_lshl_add_u64 v[154:155], s[10:11], 0, v[140:141]
	s_add_i32 m0, s14, 0x2000
	s_nop 0
	global_load_lds_dwordx4 v[154:155], off
	v_lshl_add_u64 v[154:155], v[186:187], 0, s[96:97]
	s_mov_b32 m0, s40
	s_nop 0
	global_load_lds_dwordx4 v[154:155], off
	v_lshl_add_u64 v[154:155], v[188:189], 0, s[96:97]
	s_mov_b32 m0, s41
	s_nop 0
	global_load_lds_dwordx4 v[154:155], off
	s_waitcnt vmcnt(8)
	s_waitcnt lgkmcnt(0)
	s_barrier
	s_waitcnt lgkmcnt(0)
	v_mfma_f32_16x16x32_bf16 v[60:63], v[128:131], v[174:177], v[60:63]
	v_mfma_f32_16x16x32_bf16 v[60:63], v[132:135], v[178:181], v[60:63]
	v_mfma_f32_16x16x32_bf16 v[44:47], v[128:131], v[190:193], v[44:47]
	v_mfma_f32_16x16x32_bf16 v[44:47], v[132:135], v[194:197], v[44:47]
	v_mfma_f32_16x16x32_bf16 v[28:31], v[128:131], v[198:201], v[28:31]
	v_mfma_f32_16x16x32_bf16 v[28:31], v[132:135], v[202:205], v[28:31]
	v_mfma_f32_16x16x32_bf16 v[12:15], v[128:131], v[206:209], v[12:15]
	v_mfma_f32_16x16x32_bf16 v[12:15], v[132:135], v[210:213], v[12:15]
	v_mfma_f32_16x16x32_bf16 v[56:59], v[146:149], v[174:177], v[56:59]
	v_mfma_f32_16x16x32_bf16 v[56:59], v[150:153], v[178:181], v[56:59]
	v_mfma_f32_16x16x32_bf16 v[40:43], v[146:149], v[190:193], v[40:43]
	v_mfma_f32_16x16x32_bf16 v[40:43], v[150:153], v[194:197], v[40:43]
	v_mfma_f32_16x16x32_bf16 v[24:27], v[146:149], v[198:201], v[24:27]
	v_mfma_f32_16x16x32_bf16 v[24:27], v[150:153], v[202:205], v[24:27]
	v_mfma_f32_16x16x32_bf16 v[8:11], v[146:149], v[206:209], v[8:11]
	v_mfma_f32_16x16x32_bf16 v[8:11], v[150:153], v[210:213], v[8:11]
	v_mfma_f32_16x16x32_bf16 v[52:55], v[158:161], v[174:177], v[52:55]
	v_mfma_f32_16x16x32_bf16 v[52:55], v[162:165], v[178:181], v[52:55]
	v_mfma_f32_16x16x32_bf16 v[36:39], v[158:161], v[190:193], v[36:39]
	v_mfma_f32_16x16x32_bf16 v[36:39], v[162:165], v[194:197], v[36:39]
	v_mfma_f32_16x16x32_bf16 v[20:23], v[158:161], v[198:201], v[20:23]
	v_mfma_f32_16x16x32_bf16 v[20:23], v[162:165], v[202:205], v[20:23]
	v_mfma_f32_16x16x32_bf16 v[4:7], v[158:161], v[206:209], v[4:7]
	v_mfma_f32_16x16x32_bf16 v[4:7], v[162:165], v[210:213], v[4:7]
	v_mfma_f32_16x16x32_bf16 v[48:51], v[166:169], v[174:177], v[48:51]
	v_mfma_f32_16x16x32_bf16 v[48:51], v[170:173], v[178:181], v[48:51]
	v_mfma_f32_16x16x32_bf16 v[32:35], v[166:169], v[190:193], v[32:35]
	v_mfma_f32_16x16x32_bf16 v[32:35], v[170:173], v[194:197], v[32:35]
	v_mfma_f32_16x16x32_bf16 v[16:19], v[166:169], v[198:201], v[16:19]
	v_mfma_f32_16x16x32_bf16 v[16:19], v[170:173], v[202:205], v[16:19]
	v_mfma_f32_16x16x32_bf16 v[0:3], v[166:169], v[206:209], v[0:3]
	v_mfma_f32_16x16x32_bf16 v[0:3], v[170:173], v[210:213], v[0:3]
	s_barrier
	s_add_i32 s23, s23, 2
	s_add_u32 s19, s19, 0x100
	s_addc_u32 s22, s22, 0
	s_cmpk_gt_u32 s23, 0x55
	s_mov_b64 s[10:11], s[12:13]
	s_cbranch_scc0 .LBB0_443
	s_and_b64 vcc, exec, s[86:87]
	s_cbranch_vccz .LBB0_446
	s_barrier

.LBB0_544:
	s_add_u32 s18, s6, 0xfff80080
	s_addc_u32 s19, s7, -1
	s_add_i32 s43, 0, 0x10000
	s_cmp_eq_u32 s42, 28
	s_cselect_b32 s23, s11, s19
	s_cselect_b32 s22, s38, s18
	v_add_u32_e32 v176, s43, v178
	s_cselect_b32 s19, s9, s41
	s_cselect_b32 s18, s39, s40
	s_add_i32 s46, 0, 0x14000
	ds_read_b128 v[172:175], v176
	ds_read_b128 v[180:183], v176 offset:1024
	ds_read_b128 v[190:193], v176 offset:2048
	ds_read_b128 v[194:197], v176 offset:3072
	v_add_u32_e32 v176, s46, v178
	ds_read_b128 v[198:201], v176
	ds_read_b128 v[202:205], v176 offset:1024
	ds_read_b128 v[206:209], v176 offset:2048
	ds_read_b128 v[210:213], v176 offset:3072
	v_lshl_add_u64 v[176:177], s[6:7], 0, v[168:169]
	s_add_i32 m0, s17, 0xc000
	ds_read_b128 v[214:217], v179
	ds_read_b128 v[218:221], v179 offset:1024
	ds_read_b128 v[222:225], v179 offset:2048
	ds_read_b128 v[226:229], v179 offset:3072
	ds_read_b128 v[230:233], v179 offset:4096
	ds_read_b128 v[234:237], v179 offset:5120
	ds_read_b128 v[244:247], v179 offset:6144
	ds_read_b128 v[248:251], v179 offset:7168
	global_load_lds_dwordx4 v[176:177], off
	v_lshl_add_u64 v[176:177], s[6:7], 0, v[170:171]
	s_add_i32 m0, s17, 0xe000
	s_nop 0
	global_load_lds_dwordx4 v[176:177], off
	s_waitcnt vmcnt(8)
	s_waitcnt lgkmcnt(0)
	s_barrier
	s_waitcnt lgkmcnt(0)
	v_mfma_f32_16x16x32_bf16 v[156:159], v[172:175], v[214:217], v[156:159]
	v_mfma_f32_16x16x32_bf16 v[156:159], v[180:183], v[218:221], v[156:159]
	v_mfma_f32_16x16x32_bf16 v[140:143], v[172:175], v[222:225], v[140:143]
	v_mfma_f32_16x16x32_bf16 v[140:143], v[180:183], v[226:229], v[140:143]
	v_mfma_f32_16x16x32_bf16 v[124:127], v[172:175], v[230:233], v[124:127]
	v_mfma_f32_16x16x32_bf16 v[124:127], v[180:183], v[234:237], v[124:127]
	v_mfma_f32_16x16x32_bf16 v[108:111], v[172:175], v[244:247], v[108:111]
	v_mfma_f32_16x16x32_bf16 v[108:111], v[180:183], v[248:251], v[108:111]
	v_mfma_f32_16x16x32_bf16 v[148:151], v[190:193], v[214:217], v[148:151]
	v_mfma_f32_16x16x32_bf16 v[148:151], v[194:197], v[218:221], v[148:151]
	v_mfma_f32_16x16x32_bf16 v[132:135], v[190:193], v[222:225], v[132:135]
	v_mfma_f32_16x16x32_bf16 v[132:135], v[194:197], v[226:229], v[132:135]
	v_mfma_f32_16x16x32_bf16 v[116:119], v[190:193], v[230:233], v[116:119]
	v_mfma_f32_16x16x32_bf16 v[116:119], v[194:197], v[234:237], v[116:119]
	v_mfma_f32_16x16x32_bf16 v[100:103], v[190:193], v[244:247], v[100:103]
	v_mfma_f32_16x16x32_bf16 v[100:103], v[194:197], v[248:251], v[100:103]
	v_mfma_f32_16x16x32_bf16 v[152:155], v[198:201], v[214:217], v[152:155]
	v_mfma_f32_16x16x32_bf16 v[152:155], v[202:205], v[218:221], v[152:155]
	v_mfma_f32_16x16x32_bf16 v[136:139], v[198:201], v[222:225], v[136:139]
	v_mfma_f32_16x16x32_bf16 v[136:139], v[202:205], v[226:229], v[136:139]
	v_mfma_f32_16x16x32_bf16 v[120:123], v[198:201], v[230:233], v[120:123]
	v_mfma_f32_16x16x32_bf16 v[120:123], v[202:205], v[234:237], v[120:123]
	v_mfma_f32_16x16x32_bf16 v[104:107], v[198:201], v[244:247], v[104:107]
	v_mfma_f32_16x16x32_bf16 v[104:107], v[202:205], v[248:251], v[104:107]
	v_mfma_f32_16x16x32_bf16 v[144:147], v[206:209], v[214:217], v[144:147]
	v_mfma_f32_16x16x32_bf16 v[144:147], v[210:213], v[218:221], v[144:147]
	v_mfma_f32_16x16x32_bf16 v[128:131], v[206:209], v[222:225], v[128:131]
	v_mfma_f32_16x16x32_bf16 v[128:131], v[210:213], v[226:229], v[128:131]
	v_mfma_f32_16x16x32_bf16 v[112:115], v[206:209], v[230:233], v[112:115]
	v_mfma_f32_16x16x32_bf16 v[112:115], v[210:213], v[234:237], v[112:115]
	v_mfma_f32_16x16x32_bf16 v[96:99], v[206:209], v[244:247], v[96:99]
	v_mfma_f32_16x16x32_bf16 v[96:99], v[210:213], v[248:251], v[96:99]
	s_barrier
	s_add_i32 s43, s43, s89
	v_lshl_add_u64 v[176:177], s[18:19], 0, v[164:165]
	s_mov_b32 m0, s43
	ds_read_b128 v[214:217], v179 offset:16384
	ds_read_b128 v[218:221], v179 offset:17408
	ds_read_b128 v[222:225], v179 offset:18432
	ds_read_b128 v[226:229], v179 offset:19456
	ds_read_b128 v[230:233], v179 offset:20480
	ds_read_b128 v[234:237], v179 offset:21504
	ds_read_b128 v[244:247], v179 offset:22528
	ds_read_b128 v[248:251], v179 offset:23552
	global_load_lds_dwordx4 v[176:177], off
	s_add_i32 m0, s43, 0x2000
	s_add_u32 s44, s18, 0x80000
	v_lshl_add_u64 v[238:239], s[18:19], 0, v[160:161]
	s_addc_u32 s45, s19, 0
	s_add_i32 s43, s46, s89
	global_load_lds_dwordx4 v[238:239], off
	v_lshl_add_u64 v[252:253], s[44:45], 0, v[164:165]
	s_mov_b32 m0, s43
	v_lshl_add_u64 v[186:187], s[22:23], 0, v[162:163]
	global_load_lds_dwordx4 v[252:253], off
	v_lshl_add_u64 v[252:253], s[44:45], 0, v[160:161]
	s_add_i32 m0, s43, 0x2000
	s_nop 0
	global_load_lds_dwordx4 v[252:253], off
	v_lshl_add_u64 v[252:253], s[22:23], 0, v[166:167]
	s_mov_b32 m0, s17
	s_nop 0
	global_load_lds_dwordx4 v[252:253], off
	s_mov_b32 m0, s28
	s_nop 0
	global_load_lds_dwordx4 v[186:187], off
	s_waitcnt vmcnt(8)
	s_waitcnt lgkmcnt(0)
	s_barrier
	s_waitcnt lgkmcnt(0)
	v_mfma_f32_16x16x32_bf16 v[92:95], v[172:175], v[214:217], v[92:95]
	v_mfma_f32_16x16x32_bf16 v[92:95], v[180:183], v[218:221], v[92:95]
	v_mfma_f32_16x16x32_bf16 v[76:79], v[172:175], v[222:225], v[76:79]
	v_mfma_f32_16x16x32_bf16 v[76:79], v[180:183], v[226:229], v[76:79]
	v_mfma_f32_16x16x32_bf16 v[60:63], v[172:175], v[230:233], v[60:63]
	v_mfma_f32_16x16x32_bf16 v[60:63], v[180:183], v[234:237], v[60:63]
	v_mfma_f32_16x16x32_bf16 v[44:47], v[172:175], v[244:247], v[44:47]
	v_mfma_f32_16x16x32_bf16 v[44:47], v[180:183], v[248:251], v[44:47]
	v_mfma_f32_16x16x32_bf16 v[84:87], v[190:193], v[214:217], v[84:87]
	v_mfma_f32_16x16x32_bf16 v[84:87], v[194:197], v[218:221], v[84:87]
	v_mfma_f32_16x16x32_bf16 v[68:71], v[190:193], v[222:225], v[68:71]
	v_mfma_f32_16x16x32_bf16 v[68:71], v[194:197], v[226:229], v[68:71]
	v_mfma_f32_16x16x32_bf16 v[52:55], v[190:193], v[230:233], v[52:55]
	v_mfma_f32_16x16x32_bf16 v[52:55], v[194:197], v[234:237], v[52:55]
	v_mfma_f32_16x16x32_bf16 v[36:39], v[190:193], v[244:247], v[36:39]
	v_mfma_f32_16x16x32_bf16 v[36:39], v[194:197], v[248:251], v[36:39]
	v_mfma_f32_16x16x32_bf16 v[88:91], v[198:201], v[214:217], v[88:91]
	v_mfma_f32_16x16x32_bf16 v[88:91], v[202:205], v[218:221], v[88:91]
	v_mfma_f32_16x16x32_bf16 v[72:75], v[198:201], v[222:225], v[72:75]
	v_mfma_f32_16x16x32_bf16 v[72:75], v[202:205], v[226:229], v[72:75]
	v_mfma_f32_16x16x32_bf16 v[56:59], v[198:201], v[230:233], v[56:59]
	v_mfma_f32_16x16x32_bf16 v[56:59], v[202:205], v[234:237], v[56:59]
	v_mfma_f32_16x16x32_bf16 v[40:43], v[198:201], v[244:247], v[40:43]
	v_mfma_f32_16x16x32_bf16 v[40:43], v[202:205], v[248:251], v[40:43]
	v_mfma_f32_16x16x32_bf16 v[80:83], v[206:209], v[214:217], v[80:83]
	v_mfma_f32_16x16x32_bf16 v[80:83], v[210:213], v[218:221], v[80:83]
	v_mfma_f32_16x16x32_bf16 v[64:67], v[206:209], v[222:225], v[64:67]
	v_mfma_f32_16x16x32_bf16 v[64:67], v[210:213], v[226:229], v[64:67]
	v_mfma_f32_16x16x32_bf16 v[48:51], v[206:209], v[230:233], v[48:51]
	v_mfma_f32_16x16x32_bf16 v[48:51], v[210:213], v[234:237], v[48:51]
	v_mfma_f32_16x16x32_bf16 v[32:35], v[206:209], v[244:247], v[32:35]
	v_mfma_f32_16x16x32_bf16 v[32:35], v[210:213], v[248:251], v[32:35]
	s_barrier
	s_add_i32 s43, 0, 0x18000
	v_add_u32_e32 v184, s43, v178
	s_add_i32 s44, 0, 0x1c000
	ds_read_b128 v[172:175], v184
	ds_read_b128 v[180:183], v184 offset:1024
	ds_read_b128 v[190:193], v184 offset:2048
	ds_read_b128 v[194:197], v184 offset:3072
	v_add_u32_e32 v184, s44, v178
	ds_read_b128 v[198:201], v184
	ds_read_b128 v[202:205], v184 offset:1024
	ds_read_b128 v[206:209], v184 offset:2048
	ds_read_b128 v[210:213], v184 offset:3072
	s_add_u32 s22, s22, 0x80000
	s_addc_u32 s23, s23, 0
	s_mov_b32 m0, s29
	v_lshl_add_u64 v[188:189], s[22:23], 0, v[166:167]
	ds_read_b128 v[214:217], v179 offset:32768
	ds_read_b128 v[218:221], v179 offset:33792
	ds_read_b128 v[222:225], v179 offset:34816
	ds_read_b128 v[226:229], v179 offset:35840
	ds_read_b128 v[230:233], v179 offset:36864
	ds_read_b128 v[234:237], v179 offset:37888
	ds_read_b128 v[244:247], v179 offset:38912
	ds_read_b128 v[248:251], v179 offset:39936
	global_load_lds_dwordx4 v[188:189], off
	v_lshl_add_u64 v[188:189], s[22:23], 0, v[162:163]
	s_mov_b32 m0, s30
	s_nop 0
	global_load_lds_dwordx4 v[188:189], off
	s_waitcnt vmcnt(8)
	s_waitcnt lgkmcnt(0)
	s_barrier
	s_waitcnt lgkmcnt(0)
	v_mfma_f32_16x16x32_bf16 v[156:159], v[172:175], v[214:217], v[156:159]
	v_mfma_f32_16x16x32_bf16 v[156:159], v[180:183], v[218:221], v[156:159]
	v_mfma_f32_16x16x32_bf16 v[140:143], v[172:175], v[222:225], v[140:143]
	v_mfma_f32_16x16x32_bf16 v[140:143], v[180:183], v[226:229], v[140:143]
	v_mfma_f32_16x16x32_bf16 v[124:127], v[172:175], v[230:233], v[124:127]
	v_mfma_f32_16x16x32_bf16 v[124:127], v[180:183], v[234:237], v[124:127]
	v_mfma_f32_16x16x32_bf16 v[108:111], v[172:175], v[244:247], v[108:111]
	v_mfma_f32_16x16x32_bf16 v[108:111], v[180:183], v[248:251], v[108:111]
	v_mfma_f32_16x16x32_bf16 v[148:151], v[190:193], v[214:217], v[148:151]
	v_mfma_f32_16x16x32_bf16 v[148:151], v[194:197], v[218:221], v[148:151]
	v_mfma_f32_16x16x32_bf16 v[132:135], v[190:193], v[222:225], v[132:135]
	v_mfma_f32_16x16x32_bf16 v[132:135], v[194:197], v[226:229], v[132:135]
	v_mfma_f32_16x16x32_bf16 v[116:119], v[190:193], v[230:233], v[116:119]
	v_mfma_f32_16x16x32_bf16 v[116:119], v[194:197], v[234:237], v[116:119]
	v_mfma_f32_16x16x32_bf16 v[100:103], v[190:193], v[244:247], v[100:103]
	v_mfma_f32_16x16x32_bf16 v[100:103], v[194:197], v[248:251], v[100:103]
	v_mfma_f32_16x16x32_bf16 v[152:155], v[198:201], v[214:217], v[152:155]
	v_mfma_f32_16x16x32_bf16 v[152:155], v[202:205], v[218:221], v[152:155]
	v_mfma_f32_16x16x32_bf16 v[136:139], v[198:201], v[222:225], v[136:139]
	v_mfma_f32_16x16x32_bf16 v[136:139], v[202:205], v[226:229], v[136:139]
	v_mfma_f32_16x16x32_bf16 v[120:123], v[198:201], v[230:233], v[120:123]
	v_mfma_f32_16x16x32_bf16 v[120:123], v[202:205], v[234:237], v[120:123]
	v_mfma_f32_16x16x32_bf16 v[104:107], v[198:201], v[244:247], v[104:107]
	v_mfma_f32_16x16x32_bf16 v[104:107], v[202:205], v[248:251], v[104:107]
	v_mfma_f32_16x16x32_bf16 v[144:147], v[206:209], v[214:217], v[144:147]
	v_mfma_f32_16x16x32_bf16 v[144:147], v[210:213], v[218:221], v[144:147]
	v_mfma_f32_16x16x32_bf16 v[128:131], v[206:209], v[222:225], v[128:131]
	v_mfma_f32_16x16x32_bf16 v[128:131], v[210:213], v[226:229], v[128:131]
	v_mfma_f32_16x16x32_bf16 v[112:115], v[206:209], v[230:233], v[112:115]
	v_mfma_f32_16x16x32_bf16 v[112:115], v[210:213], v[234:237], v[112:115]
	v_mfma_f32_16x16x32_bf16 v[96:99], v[206:209], v[244:247], v[96:99]
	v_mfma_f32_16x16x32_bf16 v[96:99], v[210:213], v[248:251], v[96:99]
	s_barrier
	s_add_i32 s22, s43, s89
	v_lshl_add_u64 v[176:177], v[176:177], 0, s[96:97]
	s_mov_b32 m0, s22
	ds_read_b128 v[214:217], v179 offset:49152
	ds_read_b128 v[218:221], v179 offset:50176
	ds_read_b128 v[222:225], v179 offset:51200
	ds_read_b128 v[226:229], v179 offset:52224
	ds_read_b128 v[230:233], v179 offset:53248
	ds_read_b128 v[234:237], v179 offset:54272
	ds_read_b128 v[244:247], v179 offset:55296
	ds_read_b128 v[248:251], v179 offset:56320
	global_load_lds_dwordx4 v[176:177], off
	s_add_i32 m0, s22, 0x2000
	s_add_u32 s18, s18, 0x80080
	v_lshl_add_u64 v[176:177], v[238:239], 0, s[96:97]
	s_addc_u32 s19, s19, 0
	s_add_i32 s22, s44, s89
	global_load_lds_dwordx4 v[176:177], off
	v_lshl_add_u64 v[176:177], s[18:19], 0, v[164:165]
	s_mov_b32 m0, s22
	s_nop 0
	global_load_lds_dwordx4 v[176:177], off
	v_lshl_add_u64 v[176:177], s[18:19], 0, v[160:161]
	s_add_i32 m0, s22, 0x2000
	s_nop 0
	global_load_lds_dwordx4 v[176:177], off
	v_lshl_add_u64 v[176:177], v[252:253], 0, s[96:97]
	s_mov_b32 m0, s31
	s_nop 0
	global_load_lds_dwordx4 v[176:177], off
	v_lshl_add_u64 v[176:177], v[186:187], 0, s[96:97]
	s_mov_b32 m0, s34
	s_nop 0
	global_load_lds_dwordx4 v[176:177], off
	s_waitcnt vmcnt(8)
	s_waitcnt lgkmcnt(0)
	s_barrier
	s_waitcnt lgkmcnt(0)
	v_mfma_f32_16x16x32_bf16 v[92:95], v[172:175], v[214:217], v[92:95]
	v_mfma_f32_16x16x32_bf16 v[92:95], v[180:183], v[218:221], v[92:95]
	v_mfma_f32_16x16x32_bf16 v[76:79], v[172:175], v[222:225], v[76:79]
	v_mfma_f32_16x16x32_bf16 v[76:79], v[180:183], v[226:229], v[76:79]
	v_mfma_f32_16x16x32_bf16 v[60:63], v[172:175], v[230:233], v[60:63]
	v_mfma_f32_16x16x32_bf16 v[60:63], v[180:183], v[234:237], v[60:63]
	v_mfma_f32_16x16x32_bf16 v[44:47], v[172:175], v[244:247], v[44:47]
	v_mfma_f32_16x16x32_bf16 v[44:47], v[180:183], v[248:251], v[44:47]
	v_mfma_f32_16x16x32_bf16 v[84:87], v[190:193], v[214:217], v[84:87]
	v_mfma_f32_16x16x32_bf16 v[84:87], v[194:197], v[218:221], v[84:87]
	v_mfma_f32_16x16x32_bf16 v[68:71], v[190:193], v[222:225], v[68:71]
	v_mfma_f32_16x16x32_bf16 v[68:71], v[194:197], v[226:229], v[68:71]
	v_mfma_f32_16x16x32_bf16 v[52:55], v[190:193], v[230:233], v[52:55]
	v_mfma_f32_16x16x32_bf16 v[52:55], v[194:197], v[234:237], v[52:55]
	v_mfma_f32_16x16x32_bf16 v[36:39], v[190:193], v[244:247], v[36:39]
	v_mfma_f32_16x16x32_bf16 v[36:39], v[194:197], v[248:251], v[36:39]
	v_mfma_f32_16x16x32_bf16 v[88:91], v[198:201], v[214:217], v[88:91]
	v_mfma_f32_16x16x32_bf16 v[88:91], v[202:205], v[218:221], v[88:91]
	v_mfma_f32_16x16x32_bf16 v[72:75], v[198:201], v[222:225], v[72:75]
	v_mfma_f32_16x16x32_bf16 v[72:75], v[202:205], v[226:229], v[72:75]
	v_mfma_f32_16x16x32_bf16 v[56:59], v[198:201], v[230:233], v[56:59]
	v_mfma_f32_16x16x32_bf16 v[56:59], v[202:205], v[234:237], v[56:59]
	v_mfma_f32_16x16x32_bf16 v[40:43], v[198:201], v[244:247], v[40:43]
	v_mfma_f32_16x16x32_bf16 v[40:43], v[202:205], v[248:251], v[40:43]
	v_mfma_f32_16x16x32_bf16 v[80:83], v[206:209], v[214:217], v[80:83]
	v_mfma_f32_16x16x32_bf16 v[80:83], v[210:213], v[218:221], v[80:83]
	v_mfma_f32_16x16x32_bf16 v[64:67], v[206:209], v[222:225], v[64:67]
	v_mfma_f32_16x16x32_bf16 v[64:67], v[210:213], v[226:229], v[64:67]
	v_mfma_f32_16x16x32_bf16 v[48:51], v[206:209], v[230:233], v[48:51]
	v_mfma_f32_16x16x32_bf16 v[48:51], v[210:213], v[234:237], v[48:51]
	v_mfma_f32_16x16x32_bf16 v[32:35], v[206:209], v[244:247], v[32:35]
	v_mfma_f32_16x16x32_bf16 v[32:35], v[210:213], v[248:251], v[32:35]
	s_barrier
	s_add_i32 s42, s42, 2
	s_add_u32 s6, s6, 0x100
	s_addc_u32 s7, s7, 0
	s_add_u32 s40, s40, 0x100
	s_addc_u32 s41, s41, 0
	s_cmp_gt_u32 s42, 29
	s_cbranch_scc0 .LBB0_544
	s_and_b64 vcc, exec, s[86:87]
	s_cbranch_vccz .LBB0_547
	s_barrier

.LBB0_570:
	s_ashr_i32 s9, s8, 31
	s_lshl_b64 s[10:11], s[8:9], 17
	s_add_u32 s10, s24, s10
	s_addc_u32 s11, s25, s11
	s_and_b64 s[14:15], s[4:5], exec
	s_cselect_b32 s23, s11, s17
	s_cselect_b32 s22, s10, s16
	s_ashr_i32 s7, s6, 31
	s_lshl_b64 s[14:15], s[6:7], 17
	s_add_u32 s14, s26, s14
	s_addc_u32 s15, s27, s15
	s_and_b64 s[20:21], s[4:5], exec
	s_cselect_b32 s21, s15, s19
	s_cselect_b32 s20, s14, s18
	s_add_i32 s40, 0, 0x10000
	s_add_i32 s41, 0, 0x14000
	v_add_u32_e32 v212, s40, v134
	v_add_u32_e32 v213, s41, v134
	ds_read_b128 v[0:3], v212
	ds_read_b128 v[4:7], v212 offset:1024
	ds_read_b128 v[8:11], v212 offset:2048
	ds_read_b128 v[12:15], v212 offset:3072
	ds_read_b128 v[16:19], v213
	ds_read_b128 v[20:23], v213 offset:1024
	ds_read_b128 v[24:27], v213 offset:2048
	ds_read_b128 v[28:31], v213 offset:3072
	s_add_u32 s38, s16, 0x10080
	s_addc_u32 s39, s17, 0
	s_add_i32 s42, s13, 0xc000
	v_lshl_add_u64 v[64:65], s[38:39], 0, v[132:133]
	s_mov_b32 m0, s42
	s_add_i32 s7, s13, 0xe000
	s_waitcnt lgkmcnt(0)
	ds_read_b128 v[32:35], v135
	ds_read_b128 v[36:39], v135 offset:1024
	ds_read_b128 v[40:43], v135 offset:2048
	ds_read_b128 v[44:47], v135 offset:3072
	ds_read_b128 v[48:51], v135 offset:4096
	ds_read_b128 v[52:55], v135 offset:5120
	ds_read_b128 v[56:59], v135 offset:6144
	ds_read_b128 v[60:63], v135 offset:7168
	global_load_lds_dwordx4 v[64:65], off
	v_lshl_add_u64 v[64:65], s[38:39], 0, v[130:131]
	s_mov_b32 m0, s7
	s_nop 0
	global_load_lds_dwordx4 v[64:65], off
	s_waitcnt vmcnt(8)
	s_waitcnt lgkmcnt(0)
	s_barrier
	s_waitcnt lgkmcnt(0)
	v_mfma_f32_16x16x32_bf16 v[64:67], v[0:3], v[32:35], 0
	v_mfma_f32_16x16x32_bf16 v[64:67], v[4:7], v[36:39], v[64:67]
	v_mfma_f32_16x16x32_bf16 v[72:75], v[0:3], v[40:43], 0
	v_mfma_f32_16x16x32_bf16 v[72:75], v[4:7], v[44:47], v[72:75]
	v_mfma_f32_16x16x32_bf16 v[80:83], v[0:3], v[48:51], 0
	v_mfma_f32_16x16x32_bf16 v[80:83], v[4:7], v[52:55], v[80:83]
	v_mfma_f32_16x16x32_bf16 v[88:91], v[0:3], v[56:59], 0
	v_mfma_f32_16x16x32_bf16 v[88:91], v[4:7], v[60:63], v[88:91]
	v_mfma_f32_16x16x32_bf16 v[68:71], v[8:11], v[32:35], 0
	v_mfma_f32_16x16x32_bf16 v[68:71], v[12:15], v[36:39], v[68:71]
	v_mfma_f32_16x16x32_bf16 v[76:79], v[8:11], v[40:43], 0
	v_mfma_f32_16x16x32_bf16 v[76:79], v[12:15], v[44:47], v[76:79]
	v_mfma_f32_16x16x32_bf16 v[84:87], v[8:11], v[48:51], 0
	v_mfma_f32_16x16x32_bf16 v[84:87], v[12:15], v[52:55], v[84:87]
	v_mfma_f32_16x16x32_bf16 v[92:95], v[8:11], v[56:59], 0
	v_mfma_f32_16x16x32_bf16 v[92:95], v[12:15], v[60:63], v[92:95]
	v_mfma_f32_16x16x32_bf16 v[96:99], v[16:19], v[32:35], 0
	v_mfma_f32_16x16x32_bf16 v[32:35], v[24:27], v[32:35], 0
	v_mfma_f32_16x16x32_bf16 v[96:99], v[20:23], v[36:39], v[96:99]
	v_mfma_f32_16x16x32_bf16 v[32:35], v[28:31], v[36:39], v[32:35]
	v_mfma_f32_16x16x32_bf16 v[36:39], v[16:19], v[40:43], 0
	v_mfma_f32_16x16x32_bf16 v[40:43], v[24:27], v[40:43], 0
	v_mfma_f32_16x16x32_bf16 v[36:39], v[20:23], v[44:47], v[36:39]
	v_mfma_f32_16x16x32_bf16 v[40:43], v[28:31], v[44:47], v[40:43]
	v_mfma_f32_16x16x32_bf16 v[44:47], v[16:19], v[48:51], 0
	v_mfma_f32_16x16x32_bf16 v[48:51], v[24:27], v[48:51], 0
	v_mfma_f32_16x16x32_bf16 v[44:47], v[20:23], v[52:55], v[44:47]
	v_mfma_f32_16x16x32_bf16 v[48:51], v[28:31], v[52:55], v[48:51]
	v_mfma_f32_16x16x32_bf16 v[52:55], v[16:19], v[56:59], 0
	v_mfma_f32_16x16x32_bf16 v[56:59], v[24:27], v[56:59], 0
	v_mfma_f32_16x16x32_bf16 v[52:55], v[20:23], v[60:63], v[52:55]
	v_mfma_f32_16x16x32_bf16 v[56:59], v[28:31], v[60:63], v[56:59]
	s_barrier
	s_add_i32 s40, s40, s89
	v_lshl_add_u64 v[186:187], s[18:19], 0, v[184:185]
	s_add_i32 s9, s40, 0x2000
	v_lshl_add_u64 v[136:137], v[186:187], 0, s[48:49]
	s_mov_b32 m0, s40
	v_lshl_add_u64 v[188:189], s[18:19], 0, v[128:129]
	s_add_u32 s44, s18, 0x10100
	ds_read_b128 v[60:63], v135 offset:16384
	ds_read_b128 v[100:103], v135 offset:17408
	ds_read_b128 v[104:107], v135 offset:18432
	ds_read_b128 v[108:111], v135 offset:19456
	ds_read_b128 v[112:115], v135 offset:20480
	ds_read_b128 v[116:119], v135 offset:21504
	ds_read_b128 v[120:123], v135 offset:22528
	ds_read_b128 v[124:127], v135 offset:23552
	global_load_lds_dwordx4 v[136:137], off
	v_lshl_add_u64 v[136:137], v[188:189], 0, s[48:49]
	s_mov_b32 m0, s9
	s_addc_u32 s45, s19, 0
	s_add_i32 s38, s41, s89
	global_load_lds_dwordx4 v[136:137], off
	v_lshl_add_u64 v[136:137], s[44:45], 0, v[184:185]
	s_mov_b32 m0, s38
	s_add_i32 s39, s38, 0x2000
	global_load_lds_dwordx4 v[136:137], off
	v_lshl_add_u64 v[136:137], s[44:45], 0, v[128:129]
	s_mov_b32 m0, s39
	v_lshl_add_u64 v[206:207], s[16:17], 0, v[132:133]
	global_load_lds_dwordx4 v[136:137], off
	v_lshl_add_u64 v[136:137], v[206:207], 0, s[48:49]
	s_mov_b32 m0, s13
	v_lshl_add_u64 v[208:209], s[16:17], 0, v[130:131]
	global_load_lds_dwordx4 v[136:137], off
	v_lshl_add_u64 v[136:137], v[208:209], 0, s[48:49]
	s_mov_b32 m0, s28
	s_nop 0
	global_load_lds_dwordx4 v[136:137], off
	s_waitcnt vmcnt(8)
	s_waitcnt lgkmcnt(0)
	s_barrier
	s_waitcnt lgkmcnt(0)
	v_mfma_f32_16x16x32_bf16 v[136:139], v[0:3], v[60:63], 0
	v_mfma_f32_16x16x32_bf16 v[144:147], v[0:3], v[104:107], 0
	v_mfma_f32_16x16x32_bf16 v[152:155], v[0:3], v[112:115], 0
	v_mfma_f32_16x16x32_bf16 v[0:3], v[0:3], v[120:123], 0
	v_mfma_f32_16x16x32_bf16 v[136:139], v[4:7], v[100:103], v[136:139]
	v_mfma_f32_16x16x32_bf16 v[144:147], v[4:7], v[108:111], v[144:147]
	v_mfma_f32_16x16x32_bf16 v[152:155], v[4:7], v[116:119], v[152:155]
	v_mfma_f32_16x16x32_bf16 v[0:3], v[4:7], v[124:127], v[0:3]
	v_mfma_f32_16x16x32_bf16 v[4:7], v[8:11], v[120:123], 0
	v_mfma_f32_16x16x32_bf16 v[140:143], v[8:11], v[60:63], 0
	v_mfma_f32_16x16x32_bf16 v[148:151], v[8:11], v[104:107], 0
	v_mfma_f32_16x16x32_bf16 v[156:159], v[8:11], v[112:115], 0
	v_mfma_f32_16x16x32_bf16 v[4:7], v[12:15], v[124:127], v[4:7]
	v_mfma_f32_16x16x32_bf16 v[140:143], v[12:15], v[100:103], v[140:143]
	v_mfma_f32_16x16x32_bf16 v[148:151], v[12:15], v[108:111], v[148:151]
	v_mfma_f32_16x16x32_bf16 v[156:159], v[12:15], v[116:119], v[156:159]
	v_mfma_f32_16x16x32_bf16 v[8:11], v[16:19], v[60:63], 0
	v_mfma_f32_16x16x32_bf16 v[12:15], v[24:27], v[60:63], 0
	v_mfma_f32_16x16x32_bf16 v[8:11], v[20:23], v[100:103], v[8:11]
	v_mfma_f32_16x16x32_bf16 v[12:15], v[28:31], v[100:103], v[12:15]
	v_mfma_f32_16x16x32_bf16 v[60:63], v[16:19], v[104:107], 0
	v_mfma_f32_16x16x32_bf16 v[100:103], v[24:27], v[104:107], 0
	v_mfma_f32_16x16x32_bf16 v[104:107], v[16:19], v[112:115], 0
	v_mfma_f32_16x16x32_bf16 v[16:19], v[16:19], v[120:123], 0
	v_mfma_f32_16x16x32_bf16 v[60:63], v[20:23], v[108:111], v[60:63]
	v_mfma_f32_16x16x32_bf16 v[100:103], v[28:31], v[108:111], v[100:103]
	v_mfma_f32_16x16x32_bf16 v[104:107], v[20:23], v[116:119], v[104:107]
	v_mfma_f32_16x16x32_bf16 v[108:111], v[24:27], v[112:115], 0
	v_mfma_f32_16x16x32_bf16 v[16:19], v[20:23], v[124:127], v[16:19]
	v_mfma_f32_16x16x32_bf16 v[20:23], v[24:27], v[120:123], 0
	v_mfma_f32_16x16x32_bf16 v[108:111], v[28:31], v[116:119], v[108:111]
	v_mfma_f32_16x16x32_bf16 v[20:23], v[28:31], v[124:127], v[20:23]
	s_barrier
	s_add_i32 s43, 0, 0x18000
	s_add_i32 s46, 0, 0x1c000
	v_add_u32_e32 v222, s43, v134
	v_add_u32_e32 v223, s46, v134
	ds_read_b128 v[24:27], v222
	ds_read_b128 v[28:31], v222 offset:1024
	ds_read_b128 v[112:115], v222 offset:2048
	ds_read_b128 v[116:119], v222 offset:3072
	ds_read_b128 v[120:123], v223
	ds_read_b128 v[124:127], v223 offset:1024
	ds_read_b128 v[160:163], v223 offset:2048
	ds_read_b128 v[164:167], v223 offset:3072
	s_add_u32 s44, s16, 0x10100
	s_addc_u32 s45, s17, 0
	s_mov_b32 m0, s29
	v_lshl_add_u64 v[210:211], s[44:45], 0, v[132:133]
	ds_read_b128 v[168:171], v135 offset:32768
	ds_read_b128 v[172:175], v135 offset:33792
	ds_read_b128 v[176:179], v135 offset:34816
	ds_read_b128 v[180:183], v135 offset:35840
	ds_read_b128 v[190:193], v135 offset:36864
	ds_read_b128 v[194:197], v135 offset:37888
	ds_read_b128 v[198:201], v135 offset:38912
	ds_read_b128 v[202:205], v135 offset:39936
	global_load_lds_dwordx4 v[210:211], off
	v_lshl_add_u64 v[210:211], s[44:45], 0, v[130:131]
	s_mov_b32 m0, s30
	s_nop 0
	global_load_lds_dwordx4 v[210:211], off
	s_waitcnt vmcnt(8)
	s_waitcnt lgkmcnt(0)
	s_barrier
	s_waitcnt lgkmcnt(0)
	v_mfma_f32_16x16x32_bf16 v[64:67], v[24:27], v[168:171], v[64:67]
	v_mfma_f32_16x16x32_bf16 v[64:67], v[28:31], v[172:175], v[64:67]
	v_mfma_f32_16x16x32_bf16 v[72:75], v[24:27], v[176:179], v[72:75]
	v_mfma_f32_16x16x32_bf16 v[72:75], v[28:31], v[180:183], v[72:75]
	v_mfma_f32_16x16x32_bf16 v[80:83], v[24:27], v[190:193], v[80:83]
	v_mfma_f32_16x16x32_bf16 v[80:83], v[28:31], v[194:197], v[80:83]
	v_mfma_f32_16x16x32_bf16 v[88:91], v[24:27], v[198:201], v[88:91]
	v_mfma_f32_16x16x32_bf16 v[88:91], v[28:31], v[202:205], v[88:91]
	v_mfma_f32_16x16x32_bf16 v[68:71], v[112:115], v[168:171], v[68:71]
	v_mfma_f32_16x16x32_bf16 v[68:71], v[116:119], v[172:175], v[68:71]
	v_mfma_f32_16x16x32_bf16 v[76:79], v[112:115], v[176:179], v[76:79]
	v_mfma_f32_16x16x32_bf16 v[76:79], v[116:119], v[180:183], v[76:79]
	v_mfma_f32_16x16x32_bf16 v[84:87], v[112:115], v[190:193], v[84:87]
	v_mfma_f32_16x16x32_bf16 v[84:87], v[116:119], v[194:197], v[84:87]
	v_mfma_f32_16x16x32_bf16 v[92:95], v[112:115], v[198:201], v[92:95]
	v_mfma_f32_16x16x32_bf16 v[92:95], v[116:119], v[202:205], v[92:95]
	v_mfma_f32_16x16x32_bf16 v[96:99], v[120:123], v[168:171], v[96:99]
	v_mfma_f32_16x16x32_bf16 v[96:99], v[124:127], v[172:175], v[96:99]
	v_mfma_f32_16x16x32_bf16 v[36:39], v[120:123], v[176:179], v[36:39]
	v_mfma_f32_16x16x32_bf16 v[36:39], v[124:127], v[180:183], v[36:39]
	v_mfma_f32_16x16x32_bf16 v[44:47], v[120:123], v[190:193], v[44:47]
	v_mfma_f32_16x16x32_bf16 v[44:47], v[124:127], v[194:197], v[44:47]
	v_mfma_f32_16x16x32_bf16 v[52:55], v[120:123], v[198:201], v[52:55]
	v_mfma_f32_16x16x32_bf16 v[52:55], v[124:127], v[202:205], v[52:55]
	v_mfma_f32_16x16x32_bf16 v[32:35], v[160:163], v[168:171], v[32:35]
	v_mfma_f32_16x16x32_bf16 v[32:35], v[164:167], v[172:175], v[32:35]
	v_mfma_f32_16x16x32_bf16 v[40:43], v[160:163], v[176:179], v[40:43]
	v_mfma_f32_16x16x32_bf16 v[40:43], v[164:167], v[180:183], v[40:43]
	v_mfma_f32_16x16x32_bf16 v[48:51], v[160:163], v[190:193], v[48:51]
	v_mfma_f32_16x16x32_bf16 v[48:51], v[164:167], v[194:197], v[48:51]
	v_mfma_f32_16x16x32_bf16 v[56:59], v[160:163], v[198:201], v[56:59]
	v_mfma_f32_16x16x32_bf16 v[56:59], v[164:167], v[202:205], v[56:59]
	s_barrier
	s_add_i32 s43, s43, s89
	s_add_i32 s41, s43, 0x2000
	v_lshl_add_u64 v[186:187], v[186:187], 0, s[50:51]
	s_mov_b32 m0, s43
	s_add_u32 s44, s18, 0x10180
	ds_read_b128 v[168:171], v135 offset:49152
	ds_read_b128 v[172:175], v135 offset:50176
	ds_read_b128 v[176:179], v135 offset:51200
	ds_read_b128 v[180:183], v135 offset:52224
	ds_read_b128 v[190:193], v135 offset:53248
	ds_read_b128 v[194:197], v135 offset:54272
	ds_read_b128 v[198:201], v135 offset:55296
	ds_read_b128 v[202:205], v135 offset:56320
	global_load_lds_dwordx4 v[186:187], off
	v_lshl_add_u64 v[186:187], v[188:189], 0, s[50:51]
	s_mov_b32 m0, s41
	s_addc_u32 s45, s19, 0
	s_add_i32 s18, s46, s89
	global_load_lds_dwordx4 v[186:187], off
	v_lshl_add_u64 v[186:187], s[44:45], 0, v[184:185]
	s_mov_b32 m0, s18
	s_add_i32 s19, s18, 0x2000
	global_load_lds_dwordx4 v[186:187], off
	v_lshl_add_u64 v[186:187], s[44:45], 0, v[128:129]
	s_mov_b32 m0, s19
	s_nop 0
	global_load_lds_dwordx4 v[186:187], off
	v_lshl_add_u64 v[186:187], v[206:207], 0, s[50:51]
	s_mov_b32 m0, s35
	s_nop 0
	global_load_lds_dwordx4 v[186:187], off
	v_lshl_add_u64 v[186:187], v[208:209], 0, s[50:51]
	s_mov_b32 m0, s36
	s_nop 0
	global_load_lds_dwordx4 v[186:187], off
	s_waitcnt vmcnt(8)
	s_waitcnt lgkmcnt(0)
	s_barrier
	s_waitcnt lgkmcnt(0)
	v_mfma_f32_16x16x32_bf16 v[0:3], v[24:27], v[198:201], v[0:3]
	v_mfma_f32_16x16x32_bf16 v[0:3], v[28:31], v[202:205], v[0:3]
	v_mfma_f32_16x16x32_bf16 v[136:139], v[24:27], v[168:171], v[136:139]
	v_mfma_f32_16x16x32_bf16 v[136:139], v[28:31], v[172:175], v[136:139]
	v_mfma_f32_16x16x32_bf16 v[144:147], v[24:27], v[176:179], v[144:147]
	v_mfma_f32_16x16x32_bf16 v[144:147], v[28:31], v[180:183], v[144:147]
	v_mfma_f32_16x16x32_bf16 v[152:155], v[24:27], v[190:193], v[152:155]
	v_mfma_f32_16x16x32_bf16 v[152:155], v[28:31], v[194:197], v[152:155]
	v_mfma_f32_16x16x32_bf16 v[4:7], v[112:115], v[198:201], v[4:7]
	v_mfma_f32_16x16x32_bf16 v[4:7], v[116:119], v[202:205], v[4:7]
	v_mfma_f32_16x16x32_bf16 v[140:143], v[112:115], v[168:171], v[140:143]
	v_mfma_f32_16x16x32_bf16 v[140:143], v[116:119], v[172:175], v[140:143]
	v_mfma_f32_16x16x32_bf16 v[148:151], v[112:115], v[176:179], v[148:151]
	v_mfma_f32_16x16x32_bf16 v[148:151], v[116:119], v[180:183], v[148:151]
	v_mfma_f32_16x16x32_bf16 v[156:159], v[112:115], v[190:193], v[156:159]
	v_mfma_f32_16x16x32_bf16 v[156:159], v[116:119], v[194:197], v[156:159]
	v_mfma_f32_16x16x32_bf16 v[8:11], v[120:123], v[168:171], v[8:11]
	v_mfma_f32_16x16x32_bf16 v[8:11], v[124:127], v[172:175], v[8:11]
	v_mfma_f32_16x16x32_bf16 v[24:27], v[120:123], v[176:179], v[60:63]
	v_mfma_f32_16x16x32_bf16 v[24:27], v[124:127], v[180:183], v[24:27]
	v_mfma_f32_16x16x32_bf16 v[60:63], v[120:123], v[190:193], v[104:107]
	v_mfma_f32_16x16x32_bf16 v[60:63], v[124:127], v[194:197], v[60:63]
	v_mfma_f32_16x16x32_bf16 v[16:19], v[120:123], v[198:201], v[16:19]
	v_mfma_f32_16x16x32_bf16 v[16:19], v[124:127], v[202:205], v[16:19]
	v_mfma_f32_16x16x32_bf16 v[12:15], v[160:163], v[168:171], v[12:15]
	v_mfma_f32_16x16x32_bf16 v[12:15], v[164:167], v[172:175], v[12:15]
	v_mfma_f32_16x16x32_bf16 v[28:31], v[160:163], v[176:179], v[100:103]
	v_mfma_f32_16x16x32_bf16 v[28:31], v[164:167], v[180:183], v[28:31]
	v_mfma_f32_16x16x32_bf16 v[100:103], v[160:163], v[190:193], v[108:111]
	v_mfma_f32_16x16x32_bf16 v[100:103], v[164:167], v[194:197], v[100:103]
	v_mfma_f32_16x16x32_bf16 v[20:23], v[160:163], v[198:201], v[20:23]
	v_mfma_f32_16x16x32_bf16 v[20:23], v[164:167], v[202:205], v[20:23]
	s_barrier
	ds_read_b128 v[104:107], v212
	ds_read_b128 v[108:111], v212 offset:1024
	ds_read_b128 v[112:115], v212 offset:2048
	ds_read_b128 v[116:119], v212 offset:3072
	ds_read_b128 v[120:123], v213
	ds_read_b128 v[124:127], v213 offset:1024
	ds_read_b128 v[160:163], v213 offset:2048
	ds_read_b128 v[164:167], v213 offset:3072
	s_add_u32 s16, s16, 0x10180
	s_addc_u32 s17, s17, 0
	s_mov_b32 m0, s42
	v_lshl_add_u64 v[186:187], s[16:17], 0, v[132:133]
	ds_read_b128 v[168:171], v135
	ds_read_b128 v[172:175], v135 offset:1024
	ds_read_b128 v[176:179], v135 offset:2048
	ds_read_b128 v[180:183], v135 offset:3072
	ds_read_b128 v[190:193], v135 offset:4096
	ds_read_b128 v[194:197], v135 offset:5120
	ds_read_b128 v[198:201], v135 offset:6144
	ds_read_b128 v[202:205], v135 offset:7168
	global_load_lds_dwordx4 v[186:187], off
	v_lshl_add_u64 v[186:187], s[16:17], 0, v[130:131]
	s_mov_b32 m0, s7
	s_nop 0
	global_load_lds_dwordx4 v[186:187], off
	s_waitcnt vmcnt(8)
	s_waitcnt lgkmcnt(0)
	s_barrier
	s_waitcnt lgkmcnt(0)
	v_mfma_f32_16x16x32_bf16 v[64:67], v[104:107], v[168:171], v[64:67]
	v_mfma_f32_16x16x32_bf16 v[68:71], v[112:115], v[168:171], v[68:71]
	v_mfma_f32_16x16x32_bf16 v[72:75], v[104:107], v[176:179], v[72:75]
	v_mfma_f32_16x16x32_bf16 v[76:79], v[112:115], v[176:179], v[76:79]
	v_mfma_f32_16x16x32_bf16 v[80:83], v[104:107], v[190:193], v[80:83]
	v_mfma_f32_16x16x32_bf16 v[84:87], v[112:115], v[190:193], v[84:87]
	v_mfma_f32_16x16x32_bf16 v[88:91], v[104:107], v[198:201], v[88:91]
	v_mfma_f32_16x16x32_bf16 v[64:67], v[108:111], v[172:175], v[64:67]
	v_mfma_f32_16x16x32_bf16 v[68:71], v[116:119], v[172:175], v[68:71]
	v_mfma_f32_16x16x32_bf16 v[72:75], v[108:111], v[180:183], v[72:75]
	v_mfma_f32_16x16x32_bf16 v[76:79], v[116:119], v[180:183], v[76:79]
	v_mfma_f32_16x16x32_bf16 v[80:83], v[108:111], v[194:197], v[80:83]
	v_mfma_f32_16x16x32_bf16 v[84:87], v[116:119], v[194:197], v[84:87]
	v_mfma_f32_16x16x32_bf16 v[206:209], v[108:111], v[202:205], v[88:91]
	v_mfma_f32_16x16x32_bf16 v[88:91], v[112:115], v[198:201], v[92:95]
	v_mfma_f32_16x16x32_bf16 v[210:213], v[116:119], v[202:205], v[88:91]
	v_mfma_f32_16x16x32_bf16 v[88:91], v[120:123], v[168:171], v[96:99]
	v_mfma_f32_16x16x32_bf16 v[32:35], v[160:163], v[168:171], v[32:35]
	v_mfma_f32_16x16x32_bf16 v[36:39], v[120:123], v[176:179], v[36:39]
	v_mfma_f32_16x16x32_bf16 v[40:43], v[160:163], v[176:179], v[40:43]
	v_mfma_f32_16x16x32_bf16 v[44:47], v[120:123], v[190:193], v[44:47]
	v_mfma_f32_16x16x32_bf16 v[48:51], v[160:163], v[190:193], v[48:51]
	v_mfma_f32_16x16x32_bf16 v[52:55], v[120:123], v[198:201], v[52:55]
	v_mfma_f32_16x16x32_bf16 v[96:99], v[124:127], v[172:175], v[88:91]
	v_mfma_f32_16x16x32_bf16 v[32:35], v[164:167], v[172:175], v[32:35]
	v_mfma_f32_16x16x32_bf16 v[36:39], v[124:127], v[180:183], v[36:39]
	v_mfma_f32_16x16x32_bf16 v[40:43], v[164:167], v[180:183], v[40:43]
	v_mfma_f32_16x16x32_bf16 v[44:47], v[124:127], v[194:197], v[44:47]
	v_mfma_f32_16x16x32_bf16 v[48:51], v[164:167], v[194:197], v[48:51]
	v_mfma_f32_16x16x32_bf16 v[52:55], v[124:127], v[202:205], v[52:55]
	v_mfma_f32_16x16x32_bf16 v[56:59], v[160:163], v[198:201], v[56:59]
	v_mfma_f32_16x16x32_bf16 v[168:171], v[164:167], v[202:205], v[56:59]
	s_barrier
	s_mov_b32 m0, s40
	v_lshl_add_u64 v[186:187], s[20:21], 0, v[184:185]
	s_add_u32 s16, s20, 0x10000
	s_nop 1
	ds_read_b128 v[56:59], v135 offset:16384
	ds_read_b128 v[88:91], v135 offset:17408
	ds_read_b128 v[92:95], v135 offset:18432
	ds_read_b128 v[172:175], v135 offset:19456
	ds_read_b128 v[176:179], v135 offset:20480
	ds_read_b128 v[180:183], v135 offset:21504
	ds_read_b128 v[190:193], v135 offset:22528
	ds_read_b128 v[194:197], v135 offset:23552
	global_load_lds_dwordx4 v[186:187], off
	v_lshl_add_u64 v[188:189], s[20:21], 0, v[128:129]
	s_mov_b32 m0, s9
	s_addc_u32 s17, s21, 0
	global_load_lds_dwordx4 v[188:189], off
	v_lshl_add_u64 v[198:199], s[16:17], 0, v[184:185]
	s_mov_b32 m0, s38
	v_lshl_add_u64 v[238:239], s[22:23], 0, v[132:133]
	global_load_lds_dwordx4 v[198:199], off
	v_lshl_add_u64 v[198:199], s[16:17], 0, v[128:129]
	s_mov_b32 m0, s39
	v_lshl_add_u64 v[252:253], s[22:23], 0, v[130:131]
	global_load_lds_dwordx4 v[198:199], off
	s_mov_b32 m0, s13
	s_nop 0
	global_load_lds_dwordx4 v[238:239], off
	s_mov_b32 m0, s28
	s_nop 0
	global_load_lds_dwordx4 v[252:253], off
	s_waitcnt vmcnt(8)
	s_waitcnt lgkmcnt(0)
	s_barrier
	s_waitcnt lgkmcnt(0)
	v_mfma_f32_16x16x32_bf16 v[0:3], v[104:107], v[190:193], v[0:3]
	v_mfma_f32_16x16x32_bf16 v[0:3], v[108:111], v[194:197], v[0:3]
	v_mfma_f32_16x16x32_bf16 v[136:139], v[104:107], v[56:59], v[136:139]
	v_mfma_f32_16x16x32_bf16 v[136:139], v[108:111], v[88:91], v[136:139]
	v_mfma_f32_16x16x32_bf16 v[144:147], v[104:107], v[92:95], v[144:147]
	v_mfma_f32_16x16x32_bf16 v[144:147], v[108:111], v[172:175], v[144:147]
	v_mfma_f32_16x16x32_bf16 v[152:155], v[104:107], v[176:179], v[152:155]
	v_mfma_f32_16x16x32_bf16 v[152:155], v[108:111], v[180:183], v[152:155]
	v_mfma_f32_16x16x32_bf16 v[4:7], v[112:115], v[190:193], v[4:7]
	v_mfma_f32_16x16x32_bf16 v[4:7], v[116:119], v[194:197], v[4:7]
	v_mfma_f32_16x16x32_bf16 v[140:143], v[112:115], v[56:59], v[140:143]
	v_mfma_f32_16x16x32_bf16 v[140:143], v[116:119], v[88:91], v[140:143]
	v_mfma_f32_16x16x32_bf16 v[148:151], v[112:115], v[92:95], v[148:151]
	v_mfma_f32_16x16x32_bf16 v[148:151], v[116:119], v[172:175], v[148:151]
	v_mfma_f32_16x16x32_bf16 v[156:159], v[112:115], v[176:179], v[156:159]
	v_mfma_f32_16x16x32_bf16 v[156:159], v[116:119], v[180:183], v[156:159]
	v_mfma_f32_16x16x32_bf16 v[8:11], v[120:123], v[56:59], v[8:11]
	v_mfma_f32_16x16x32_bf16 v[198:201], v[124:127], v[88:91], v[8:11]
	v_mfma_f32_16x16x32_bf16 v[8:11], v[160:163], v[56:59], v[12:15]
	v_mfma_f32_16x16x32_bf16 v[202:205], v[164:167], v[88:91], v[8:11]
	v_mfma_f32_16x16x32_bf16 v[8:11], v[120:123], v[92:95], v[24:27]
	v_mfma_f32_16x16x32_bf16 v[214:217], v[124:127], v[172:175], v[8:11]
	v_mfma_f32_16x16x32_bf16 v[8:11], v[160:163], v[92:95], v[28:31]
	v_mfma_f32_16x16x32_bf16 v[172:175], v[164:167], v[172:175], v[8:11]
	v_mfma_f32_16x16x32_bf16 v[8:11], v[120:123], v[176:179], v[60:63]
	v_mfma_f32_16x16x32_bf16 v[218:221], v[124:127], v[180:183], v[8:11]
	v_mfma_f32_16x16x32_bf16 v[8:11], v[160:163], v[176:179], v[100:103]
	v_mfma_f32_16x16x32_bf16 v[176:179], v[164:167], v[180:183], v[8:11]
	v_mfma_f32_16x16x32_bf16 v[8:11], v[120:123], v[190:193], v[16:19]
	v_mfma_f32_16x16x32_bf16 v[180:183], v[124:127], v[194:197], v[8:11]
	v_mfma_f32_16x16x32_bf16 v[8:11], v[160:163], v[190:193], v[20:23]
	v_mfma_f32_16x16x32_bf16 v[160:163], v[164:167], v[194:197], v[8:11]
	s_barrier
	s_nop 4
	ds_read_b128 v[8:11], v222
	ds_read_b128 v[12:15], v222 offset:1024
	ds_read_b128 v[16:19], v222 offset:2048
	ds_read_b128 v[20:23], v222 offset:3072
	ds_read_b128 v[164:167], v223
	ds_read_b128 v[190:193], v223 offset:1024
	ds_read_b128 v[194:197], v223 offset:2048
	ds_read_b128 v[222:225], v223 offset:3072
	s_add_u32 s16, s22, 0x10000
	s_addc_u32 s17, s23, 0
	s_mov_b32 m0, s29
	v_lshl_add_u64 v[56:57], s[16:17], 0, v[132:133]
	ds_read_b128 v[24:27], v135 offset:32768
	ds_read_b128 v[28:31], v135 offset:33792
	ds_read_b128 v[100:103], v135 offset:34816
	ds_read_b128 v[226:229], v135 offset:35840
	ds_read_b128 v[230:233], v135 offset:36864
	ds_read_b128 v[234:237], v135 offset:37888
	ds_read_b128 v[244:247], v135 offset:38912
	ds_read_b128 v[248:251], v135 offset:39936
	global_load_lds_dwordx4 v[56:57], off
	v_lshl_add_u64 v[56:57], s[16:17], 0, v[130:131]
	s_mov_b32 m0, s30
	s_nop 0
	global_load_lds_dwordx4 v[56:57], off
	s_waitcnt vmcnt(8)
	s_waitcnt lgkmcnt(0)
	s_barrier
	s_waitcnt lgkmcnt(0)
	v_mfma_f32_16x16x32_bf16 v[56:59], v[8:11], v[24:27], v[64:67]
	v_mfma_f32_16x16x32_bf16 v[120:123], v[12:15], v[28:31], v[56:59]
	v_mfma_f32_16x16x32_bf16 v[56:59], v[16:19], v[24:27], v[68:71]
	v_mfma_f32_16x16x32_bf16 v[124:127], v[20:23], v[28:31], v[56:59]
	v_mfma_f32_16x16x32_bf16 v[56:59], v[8:11], v[100:103], v[72:75]
	v_mfma_f32_16x16x32_bf16 v[104:107], v[12:15], v[226:229], v[56:59]
	v_mfma_f32_16x16x32_bf16 v[56:59], v[16:19], v[100:103], v[76:79]
	v_mfma_f32_16x16x32_bf16 v[108:111], v[20:23], v[226:229], v[56:59]
	v_mfma_f32_16x16x32_bf16 v[56:59], v[8:11], v[230:233], v[80:83]
	v_mfma_f32_16x16x32_bf16 v[88:91], v[12:15], v[234:237], v[56:59]
	v_mfma_f32_16x16x32_bf16 v[56:59], v[16:19], v[230:233], v[84:87]
	v_mfma_f32_16x16x32_bf16 v[92:95], v[20:23], v[234:237], v[56:59]
	v_mfma_f32_16x16x32_bf16 v[56:59], v[8:11], v[244:247], v[206:209]
	v_mfma_f32_16x16x32_bf16 v[60:63], v[16:19], v[244:247], v[210:213]
	v_mfma_f32_16x16x32_bf16 v[56:59], v[12:15], v[248:251], v[56:59]
	v_mfma_f32_16x16x32_bf16 v[60:63], v[20:23], v[248:251], v[60:63]
	v_mfma_f32_16x16x32_bf16 v[64:67], v[164:167], v[24:27], v[96:99]
	v_mfma_f32_16x16x32_bf16 v[24:27], v[194:197], v[24:27], v[32:35]
	v_mfma_f32_16x16x32_bf16 v[116:119], v[222:225], v[28:31], v[24:27]
	v_mfma_f32_16x16x32_bf16 v[24:27], v[164:167], v[100:103], v[36:39]
	v_mfma_f32_16x16x32_bf16 v[96:99], v[190:193], v[226:229], v[24:27]
	v_mfma_f32_16x16x32_bf16 v[24:27], v[194:197], v[100:103], v[40:43]
	v_mfma_f32_16x16x32_bf16 v[100:103], v[222:225], v[226:229], v[24:27]
	v_mfma_f32_16x16x32_bf16 v[24:27], v[164:167], v[230:233], v[44:47]
	v_mfma_f32_16x16x32_bf16 v[80:83], v[190:193], v[234:237], v[24:27]
	v_mfma_f32_16x16x32_bf16 v[24:27], v[194:197], v[230:233], v[48:51]
	v_mfma_f32_16x16x32_bf16 v[84:87], v[222:225], v[234:237], v[24:27]
	v_mfma_f32_16x16x32_bf16 v[24:27], v[164:167], v[244:247], v[52:55]
	v_mfma_f32_16x16x32_bf16 v[48:51], v[190:193], v[248:251], v[24:27]
	v_mfma_f32_16x16x32_bf16 v[24:27], v[194:197], v[244:247], v[168:171]
	v_mfma_f32_16x16x32_bf16 v[112:115], v[190:193], v[28:31], v[64:67]
	v_mfma_f32_16x16x32_bf16 v[52:55], v[222:225], v[248:251], v[24:27]
	s_barrier
	s_mov_b32 m0, s43
	s_nop 2
	v_lshl_add_u64 v[24:25], v[186:187], 0, s[96:97]
	s_add_u32 s16, s20, 0x10080
	ds_read_b128 v[32:35], v135 offset:49152
	ds_read_b128 v[36:39], v135 offset:50176
	ds_read_b128 v[168:171], v135 offset:51200
	ds_read_b128 v[206:209], v135 offset:52224
	ds_read_b128 v[210:213], v135 offset:53248
	ds_read_b128 v[226:229], v135 offset:54272
	ds_read_b128 v[230:233], v135 offset:55296
	ds_read_b128 v[234:237], v135 offset:56320
	global_load_lds_dwordx4 v[24:25], off
	v_lshl_add_u64 v[24:25], v[188:189], 0, s[96:97]
	s_mov_b32 m0, s41
	s_addc_u32 s17, s21, 0
	global_load_lds_dwordx4 v[24:25], off
	v_lshl_add_u64 v[24:25], s[16:17], 0, v[184:185]
	s_mov_b32 m0, s18
	s_nop 0
	global_load_lds_dwordx4 v[24:25], off
	v_lshl_add_u64 v[24:25], s[16:17], 0, v[128:129]
	s_mov_b32 m0, s19
	s_nop 0
	global_load_lds_dwordx4 v[24:25], off
	v_lshl_add_u64 v[24:25], v[238:239], 0, s[96:97]
	s_mov_b32 m0, s35
	s_nop 0
	global_load_lds_dwordx4 v[24:25], off
	v_lshl_add_u64 v[24:25], v[252:253], 0, s[96:97]
	s_mov_b32 m0, s36
	s_nop 0
	global_load_lds_dwordx4 v[24:25], off
	s_waitcnt vmcnt(8)
	s_waitcnt lgkmcnt(0)
	s_barrier
	s_waitcnt lgkmcnt(0)
	v_mfma_f32_16x16x32_bf16 v[24:27], v[8:11], v[32:35], v[136:139]
	v_mfma_f32_16x16x32_bf16 v[72:75], v[12:15], v[36:39], v[24:27]
	v_mfma_f32_16x16x32_bf16 v[24:27], v[16:19], v[32:35], v[140:143]
	v_mfma_f32_16x16x32_bf16 v[76:79], v[20:23], v[36:39], v[24:27]
	v_mfma_f32_16x16x32_bf16 v[24:27], v[8:11], v[168:171], v[144:147]
	v_mfma_f32_16x16x32_bf16 v[40:43], v[12:15], v[206:209], v[24:27]
	v_mfma_f32_16x16x32_bf16 v[24:27], v[16:19], v[168:171], v[148:151]
	v_mfma_f32_16x16x32_bf16 v[0:3], v[8:11], v[230:233], v[0:3]
	v_mfma_f32_16x16x32_bf16 v[44:47], v[20:23], v[206:209], v[24:27]
	v_mfma_f32_16x16x32_bf16 v[24:27], v[8:11], v[210:213], v[152:155]
	v_mfma_f32_16x16x32_bf16 v[28:31], v[16:19], v[210:213], v[156:159]
	v_mfma_f32_16x16x32_bf16 v[8:11], v[12:15], v[234:237], v[0:3]
	v_mfma_f32_16x16x32_bf16 v[0:3], v[16:19], v[230:233], v[4:7]
	v_mfma_f32_16x16x32_bf16 v[24:27], v[12:15], v[226:229], v[24:27]
	v_mfma_f32_16x16x32_bf16 v[28:31], v[20:23], v[226:229], v[28:31]
	v_mfma_f32_16x16x32_bf16 v[12:15], v[20:23], v[234:237], v[0:3]
	v_mfma_f32_16x16x32_bf16 v[0:3], v[164:167], v[32:35], v[198:201]
	v_mfma_f32_16x16x32_bf16 v[64:67], v[190:193], v[36:39], v[0:3]
	v_mfma_f32_16x16x32_bf16 v[0:3], v[194:197], v[32:35], v[202:205]
	v_mfma_f32_16x16x32_bf16 v[68:71], v[222:225], v[36:39], v[0:3]
	v_mfma_f32_16x16x32_bf16 v[0:3], v[164:167], v[168:171], v[214:217]
	v_mfma_f32_16x16x32_bf16 v[32:35], v[190:193], v[206:209], v[0:3]
	v_mfma_f32_16x16x32_bf16 v[0:3], v[194:197], v[168:171], v[172:175]
	v_mfma_f32_16x16x32_bf16 v[36:39], v[222:225], v[206:209], v[0:3]
	v_mfma_f32_16x16x32_bf16 v[0:3], v[164:167], v[210:213], v[218:221]
	v_mfma_f32_16x16x32_bf16 v[16:19], v[190:193], v[226:229], v[0:3]
	v_mfma_f32_16x16x32_bf16 v[0:3], v[194:197], v[210:213], v[176:179]
	v_mfma_f32_16x16x32_bf16 v[20:23], v[222:225], v[226:229], v[0:3]
	v_mfma_f32_16x16x32_bf16 v[0:3], v[164:167], v[230:233], v[180:183]
	v_mfma_f32_16x16x32_bf16 v[4:7], v[194:197], v[230:233], v[160:163]
	v_mfma_f32_16x16x32_bf16 v[0:3], v[190:193], v[234:237], v[0:3]
	v_mfma_f32_16x16x32_bf16 v[4:7], v[222:225], v[234:237], v[4:7]
	s_barrier
	s_andn2_b64 vcc, exec, s[86:87]
	s_cbranch_vccnz .LBB0_572
	s_barrier
